# v87 + the vmcnt(N) and lgkmcnt(0) waits before each load-segment barrier merged into one s_waitcnt (20 sites)
# baseline (speedup 1.0000x reference)
; #define PG8_STAGE(bufoff, gbase, voff) do { _Pragma("unroll") for (int _i = 0; _i < 2; ++_i) \
;         __builtin_amdgcn_global_load_lds((const unsigned*)((const char*)(gbase) + (voff)[_i]), (PG8_LAS unsigned*)(lds + (bufoff) + ldsw + _i * 8192), 16, 0, 0); } while (0)
; #define PG8_LDA(dst, b, h) do { _Pragma("unroll") for (int m = 0; m < 4; ++m) _Pragma("unroll") for (int k = 0; k < 2; ++k) dst[m][k] = *(const PG8_LAS bf16x8*)(lds + PG8_SA(b, h) + aoff + m * 2048 + k * 1024); } while (0)
; #define PG8_LDB(dst, b, h) do { _Pragma("unroll") for (int n = 0; n < 2; ++n) _Pragma("unroll") for (int k = 0; k < 2; ++k) dst[n][k] = *(const PG8_LAS bf16x8*)(lds + PG8_SB(b, h) + boff + n * 2048 + k * 1024); } while (0)
; #define PG8_MMA(ai, bj, At, Bt) do { __builtin_amdgcn_s_setprio(1); _Pragma("unroll") for (int m = 0; m < 4; ++m) _Pragma("unroll") for (int n = 0; n < 2; ++n) _Pragma("unroll") for (int k = 0; k < 2; ++k) \
;         acc[ai][bj][m][n] = __builtin_amdgcn_mfma_f32_16x16x32_bf16(Bt[n][k], At[m][k], acc[ai][bj][m][n], 0, 0, 0); __builtin_amdgcn_s_setprio(0); } while (0)
; #define PG8_WAIT_V(n) asm volatile("s_waitcnt vmcnt(" #n ")" ::: "memory")
; #define PG8_WAIT_L(n) asm volatile("s_waitcnt lgkmcnt(" #n ")" ::: "memory")
; template <class Epi, class Sched, bool ALIGN_EPI = false, bool SP2 = false>
; __device__ __forceinline__ void gemm_phase(PG8_LAS unsigned char* lds, const Gemm g, const Sched& S, const Epi& E) {
;     ...
;             const bool last = (t == nt - 2);
;             const char* a1 = cA + (size_t)(t + 1) * kstep;
;             const char* a2 = last ? nA : cA + (size_t)(t + 2) * kstep; const char* b2 = last ? nB : cB + (size_t)(t + 2) * kstep;
;             const char* a3 = a2 + kstep; const char* b3 = b2 + kstep;
;             if (last && has_next) S.a_ready(nxt);
;             if constexpr (SP2) {
;             PG8_LDB(B0, 0, 0); PG8_LDB(B1, 0, 1); PG8_SCHED; PG8_LDA(At, 0, 0); PG8_STAGE(PG8_SA(1, 1), a1 + hstep, voffA);
;             PG8_WAIT_V(8); PG8_WAIT_L(0); PG8_BAR; PG8_MMA(0, 0, At, B0); PG8_MMA(0, 1, At, B1); PG8_BAR; PG8_SCHED;
;             PG8_LDA(At, 0, 1); PG8_STAGE(PG8_SB(0, 0), b2, voffB); PG8_STAGE(PG8_SB(0, 1), b2 + hstep, voffB); PG8_STAGE(PG8_SA(0, 0), a2, voffA);
;             PG8_WAIT_V(8); PG8_WAIT_L(0); PG8_BAR; PG8_MMA(1, 0, At, B0); PG8_MMA(1, 1, At, B1); PG8_BAR; PG8_SCHED;
.LBB0_139:
	s_add_u32 s36, s30, 0xfff80080
	s_addc_u32 s37, s31, -1
	s_add_i32 s70, 0, 0x10000
	s_cmp_eq_u32 s69, 28
	s_cselect_b32 s39, s25, s37
	s_cselect_b32 s38, s45, s36
	s_cselect_b32 s37, s23, s68
	s_cselect_b32 s36, s66, s67
	s_add_i32 s75, 0, 0x14000
	ds_read_b128 v[152:155], v244
	ds_read_b128 v[166:169], v244 offset:1024
	ds_read_b128 v[170:173], v244 offset:2048
	ds_read_b128 v[174:177], v244 offset:3072
	ds_read_b128 v[178:181], v245
	ds_read_b128 v[182:185], v245 offset:1024
	ds_read_b128 v[186:189], v245 offset:2048
	ds_read_b128 v[190:193], v245 offset:3072
	s_add_u32 s98, s30, 0xfff80000
	s_addc_u32 s99, s31, -1
	s_mov_b32 m0, s57
	s_nop 0
	global_load_lds_dwordx4 v138, s[98:99]
	s_mov_b32 m0, s58
	s_nop 0
	global_load_lds_dwordx4 v140, s[98:99]
	s_add_i32 m0, s53, 0xc000
	ds_read_b128 v[200:203], v151
	ds_read_b128 v[204:207], v151 offset:1024
	ds_read_b128 v[208:211], v151 offset:2048
	ds_read_b128 v[212:215], v151 offset:3072
	ds_read_b128 v[216:219], v151 offset:4096
	ds_read_b128 v[220:223], v151 offset:5120
	ds_read_b128 v[224:227], v151 offset:6144
	ds_read_b128 v[228:231], v151 offset:7168
	global_load_lds_dwordx4 v138, s[30:31]
	s_add_i32 m0, s53, 0xe000
	s_nop 0
	global_load_lds_dwordx4 v140, s[30:31]
	s_waitcnt vmcnt(8) lgkmcnt(0)
	s_barrier
	v_mfma_f32_16x16x32_bf16 v[126:129], v[152:155], v[200:203], v[126:129]
	v_mfma_f32_16x16x32_bf16 v[122:125], v[170:173], v[200:203], v[122:125]
	v_mfma_f32_16x16x32_bf16 v[110:113], v[152:155], v[208:211], v[110:113]
	v_mfma_f32_16x16x32_bf16 v[106:109], v[170:173], v[208:211], v[106:109]
	v_mfma_f32_16x16x32_bf16 v[94:97], v[152:155], v[216:219], v[94:97]
	v_mfma_f32_16x16x32_bf16 v[90:93], v[170:173], v[216:219], v[90:93]
	v_mfma_f32_16x16x32_bf16 v[78:81], v[152:155], v[224:227], v[78:81]
	v_mfma_f32_16x16x32_bf16 v[74:77], v[170:173], v[224:227], v[74:77]
	v_mfma_f32_16x16x32_bf16 v[126:129], v[166:169], v[204:207], v[126:129]
	v_mfma_f32_16x16x32_bf16 v[122:125], v[174:177], v[204:207], v[122:125]
	v_mfma_f32_16x16x32_bf16 v[110:113], v[166:169], v[212:215], v[110:113]
	v_mfma_f32_16x16x32_bf16 v[106:109], v[174:177], v[212:215], v[106:109]
	v_mfma_f32_16x16x32_bf16 v[94:97], v[166:169], v[220:223], v[94:97]
	v_mfma_f32_16x16x32_bf16 v[90:93], v[174:177], v[220:223], v[90:93]
	v_mfma_f32_16x16x32_bf16 v[78:81], v[166:169], v[228:231], v[78:81]
	v_mfma_f32_16x16x32_bf16 v[74:77], v[174:177], v[228:231], v[74:77]
	v_mfma_f32_16x16x32_bf16 v[118:121], v[178:181], v[200:203], v[118:121]
	v_mfma_f32_16x16x32_bf16 v[114:117], v[186:189], v[200:203], v[114:117]
	v_mfma_f32_16x16x32_bf16 v[102:105], v[178:181], v[208:211], v[102:105]
	v_mfma_f32_16x16x32_bf16 v[98:101], v[186:189], v[208:211], v[98:101]
	v_mfma_f32_16x16x32_bf16 v[86:89], v[178:181], v[216:219], v[86:89]
	v_mfma_f32_16x16x32_bf16 v[82:85], v[186:189], v[216:219], v[82:85]
	v_mfma_f32_16x16x32_bf16 v[70:73], v[178:181], v[224:227], v[70:73]
	v_mfma_f32_16x16x32_bf16 v[66:69], v[186:189], v[224:227], v[66:69]
	v_mfma_f32_16x16x32_bf16 v[118:121], v[182:185], v[204:207], v[118:121]
	v_mfma_f32_16x16x32_bf16 v[114:117], v[190:193], v[204:207], v[114:117]
	v_mfma_f32_16x16x32_bf16 v[102:105], v[182:185], v[212:215], v[102:105]
	v_mfma_f32_16x16x32_bf16 v[98:101], v[190:193], v[212:215], v[98:101]
	v_mfma_f32_16x16x32_bf16 v[86:89], v[182:185], v[220:223], v[86:89]
	v_mfma_f32_16x16x32_bf16 v[82:85], v[190:193], v[220:223], v[82:85]
	v_mfma_f32_16x16x32_bf16 v[70:73], v[182:185], v[228:231], v[70:73]
	v_mfma_f32_16x16x32_bf16 v[66:69], v[190:193], v[228:231], v[66:69]
	s_barrier
	s_add_i32 s70, s70, s52
	s_mov_b32 m0, s70
	ds_read_b128 v[200:203], v151 offset:16384
	ds_read_b128 v[204:207], v151 offset:17408
	ds_read_b128 v[208:211], v151 offset:18432
	ds_read_b128 v[212:215], v151 offset:19456
	ds_read_b128 v[216:219], v151 offset:20480
	ds_read_b128 v[220:223], v151 offset:21504
	ds_read_b128 v[224:227], v151 offset:22528
	ds_read_b128 v[228:231], v151 offset:23552
	global_load_lds_dwordx4 v158, s[36:37]
	s_add_i32 m0, s70, 0x2000
	s_add_u32 s70, s36, 0x80000
	s_addc_u32 s71, s37, 0
	s_add_i32 s75, s75, s52
	global_load_lds_dwordx4 v134, s[36:37]
	s_mov_b32 m0, s75
	s_nop 0
	global_load_lds_dwordx4 v158, s[70:71]
	s_add_i32 m0, s75, 0x2000
	s_nop 0
	global_load_lds_dwordx4 v134, s[70:71]
	s_waitcnt vmcnt(6) lgkmcnt(0)
	s_barrier
	v_mfma_f32_16x16x32_bf16 v[62:65], v[152:155], v[200:203], v[62:65]
	v_mfma_f32_16x16x32_bf16 v[58:61], v[170:173], v[200:203], v[58:61]
	v_mfma_f32_16x16x32_bf16 v[46:49], v[152:155], v[208:211], v[46:49]
	v_mfma_f32_16x16x32_bf16 v[42:45], v[170:173], v[208:211], v[42:45]
	v_mfma_f32_16x16x32_bf16 v[30:33], v[152:155], v[216:219], v[30:33]
	v_mfma_f32_16x16x32_bf16 v[26:29], v[170:173], v[216:219], v[26:29]
	v_mfma_f32_16x16x32_bf16 v[14:17], v[152:155], v[224:227], v[14:17]
	v_mfma_f32_16x16x32_bf16 v[10:13], v[170:173], v[224:227], v[10:13]
	v_mfma_f32_16x16x32_bf16 v[62:65], v[166:169], v[204:207], v[62:65]
	v_mfma_f32_16x16x32_bf16 v[58:61], v[174:177], v[204:207], v[58:61]
	v_mfma_f32_16x16x32_bf16 v[46:49], v[166:169], v[212:215], v[46:49]
	v_mfma_f32_16x16x32_bf16 v[42:45], v[174:177], v[212:215], v[42:45]
	v_mfma_f32_16x16x32_bf16 v[30:33], v[166:169], v[220:223], v[30:33]
	v_mfma_f32_16x16x32_bf16 v[26:29], v[174:177], v[220:223], v[26:29]
	v_mfma_f32_16x16x32_bf16 v[14:17], v[166:169], v[228:231], v[14:17]
	v_mfma_f32_16x16x32_bf16 v[10:13], v[174:177], v[228:231], v[10:13]
	v_mfma_f32_16x16x32_bf16 v[54:57], v[178:181], v[200:203], v[54:57]
	v_mfma_f32_16x16x32_bf16 v[50:53], v[186:189], v[200:203], v[50:53]
	v_mfma_f32_16x16x32_bf16 v[38:41], v[178:181], v[208:211], v[38:41]
	v_mfma_f32_16x16x32_bf16 v[34:37], v[186:189], v[208:211], v[34:37]
	v_mfma_f32_16x16x32_bf16 v[22:25], v[178:181], v[216:219], v[22:25]
	v_mfma_f32_16x16x32_bf16 v[18:21], v[186:189], v[216:219], v[18:21]
	v_mfma_f32_16x16x32_bf16 v[6:9], v[178:181], v[224:227], v[6:9]
	v_mfma_f32_16x16x32_bf16 v[2:5], v[186:189], v[224:227], v[2:5]
	v_mfma_f32_16x16x32_bf16 v[54:57], v[182:185], v[204:207], v[54:57]
	v_mfma_f32_16x16x32_bf16 v[50:53], v[190:193], v[204:207], v[50:53]
	v_mfma_f32_16x16x32_bf16 v[38:41], v[182:185], v[212:215], v[38:41]
	v_mfma_f32_16x16x32_bf16 v[34:37], v[190:193], v[212:215], v[34:37]
	v_mfma_f32_16x16x32_bf16 v[22:25], v[182:185], v[220:223], v[22:25]
	v_mfma_f32_16x16x32_bf16 v[18:21], v[190:193], v[220:223], v[18:21]
	v_mfma_f32_16x16x32_bf16 v[6:9], v[182:185], v[228:231], v[6:9]
	v_mfma_f32_16x16x32_bf16 v[2:5], v[190:193], v[228:231], v[2:5]
	s_barrier
; #define PG8_STAGE(bufoff, gbase, voff) do { _Pragma("unroll") for (int _i = 0; _i < 2; ++_i) \
;         __builtin_amdgcn_global_load_lds((const unsigned*)((const char*)(gbase) + (voff)[_i]), (PG8_LAS unsigned*)(lds + (bufoff) + ldsw + _i * 8192), 16, 0, 0); } while (0)
; #define PG8_LDA(dst, b, h) do { _Pragma("unroll") for (int m = 0; m < 4; ++m) _Pragma("unroll") for (int k = 0; k < 2; ++k) dst[m][k] = *(const PG8_LAS bf16x8*)(lds + PG8_SA(b, h) + aoff + m * 2048 + k * 1024); } while (0)
; #define PG8_WAIT_V(n) asm volatile("s_waitcnt vmcnt(" #n ")" ::: "memory")
; #define PG8_WAIT_L(n) asm volatile("s_waitcnt lgkmcnt(" #n ")" ::: "memory")
; template <class Epi, class Sched, bool ALIGN_EPI = false, bool SP2 = false>
; __device__ __forceinline__ void gemm_phase(PG8_LAS unsigned char* lds, const Gemm g, const Sched& S, const Epi& E) {
;     ...
;         for (int t = 0; t < nt; t += 2) {
;             const bool last = (t == nt - 2);
;             const char* a1 = cA + (size_t)(t + 1) * kstep;
;             const char* a2 = last ? nA : cA + (size_t)(t + 2) * kstep; const char* b2 = last ? nB : cB + (size_t)(t + 2) * kstep;
;             const char* a3 = a2 + kstep; const char* b3 = b2 + kstep;
;             if (last && has_next) S.a_ready(nxt);
;             if constexpr (SP2) {
;             PG8_LDB(B0, 0, 0); PG8_LDB(B1, 0, 1); PG8_SCHED; PG8_LDA(At, 0, 0); PG8_STAGE(PG8_SA(1, 1), a1 + hstep, voffA);
;             PG8_WAIT_V(8); PG8_WAIT_L(0); PG8_BAR; PG8_MMA(0, 0, At, B0); PG8_MMA(0, 1, At, B1); PG8_BAR; PG8_SCHED;
;             PG8_LDA(At, 0, 1); PG8_STAGE(PG8_SB(0, 0), b2, voffB); PG8_STAGE(PG8_SB(0, 1), b2 + hstep, voffB); PG8_STAGE(PG8_SA(0, 0), a2, voffA);
;             PG8_WAIT_V(8); PG8_WAIT_L(0); PG8_BAR; PG8_MMA(1, 0, At, B0); PG8_MMA(1, 1, At, B1); PG8_BAR; PG8_SCHED;
;             PG8_LDB(B0, 1, 0); PG8_LDB(B1, 1, 1); PG8_SCHED; PG8_LDA(At, 1, 0); PG8_STAGE(PG8_SA(0, 1), a2 + hstep, voffA);
;             PG8_WAIT_V(8); PG8_WAIT_L(0); PG8_BAR; PG8_MMA(0, 0, At, B0); PG8_MMA(0, 1, At, B1); PG8_BAR; PG8_SCHED;
;             PG8_LDA(At, 1, 1); PG8_STAGE(PG8_SB(1, 0), b3, voffB); PG8_STAGE(PG8_SB(1, 1), b3 + hstep, voffB); PG8_STAGE(PG8_SA(1, 0), a3, voffA);
;             PG8_WAIT_V(8); PG8_WAIT_L(0); PG8_BAR; PG8_MMA(1, 0, At, B0); PG8_MMA(1, 1, At, B1); PG8_BAR; PG8_SCHED;
;     ...
;         if constexpr (ALIGN_EPI) { if (wr == 0) PG8_BAR; }
	s_add_i32 s70, 0, 0x18000
	s_add_i32 s71, 0, 0x1c000
	ds_read_b128 v[152:155], v246
	ds_read_b128 v[166:169], v246 offset:1024
	ds_read_b128 v[170:173], v246 offset:2048
	ds_read_b128 v[174:177], v246 offset:3072
	ds_read_b128 v[178:181], v247
	ds_read_b128 v[182:185], v247 offset:1024
	ds_read_b128 v[186:189], v247 offset:2048
	ds_read_b128 v[190:193], v247 offset:3072
	s_mov_b32 m0, s53
	s_nop 0
	global_load_lds_dwordx4 v130, s[38:39]
	s_mov_b32 m0, s54
	s_nop 0
	global_load_lds_dwordx4 v132, s[38:39]
	s_add_u32 s38, s38, 0x80000
	s_addc_u32 s39, s39, 0
	s_mov_b32 m0, s55
	ds_read_b128 v[200:203], v151 offset:32768
	ds_read_b128 v[204:207], v151 offset:33792
	ds_read_b128 v[208:211], v151 offset:34816
	ds_read_b128 v[212:215], v151 offset:35840
	ds_read_b128 v[216:219], v151 offset:36864
	ds_read_b128 v[220:223], v151 offset:37888
	ds_read_b128 v[224:227], v151 offset:38912
	ds_read_b128 v[228:231], v151 offset:39936
	global_load_lds_dwordx4 v130, s[38:39]
	s_mov_b32 m0, s56
	s_nop 0
	global_load_lds_dwordx4 v132, s[38:39]
	s_waitcnt vmcnt(8) lgkmcnt(0)
	s_barrier
	v_mfma_f32_16x16x32_bf16 v[126:129], v[152:155], v[200:203], v[126:129]
	v_mfma_f32_16x16x32_bf16 v[122:125], v[170:173], v[200:203], v[122:125]
	v_mfma_f32_16x16x32_bf16 v[110:113], v[152:155], v[208:211], v[110:113]
	v_mfma_f32_16x16x32_bf16 v[106:109], v[170:173], v[208:211], v[106:109]
	v_mfma_f32_16x16x32_bf16 v[94:97], v[152:155], v[216:219], v[94:97]
	v_mfma_f32_16x16x32_bf16 v[90:93], v[170:173], v[216:219], v[90:93]
	v_mfma_f32_16x16x32_bf16 v[78:81], v[152:155], v[224:227], v[78:81]
	v_mfma_f32_16x16x32_bf16 v[74:77], v[170:173], v[224:227], v[74:77]
	v_mfma_f32_16x16x32_bf16 v[126:129], v[166:169], v[204:207], v[126:129]
	v_mfma_f32_16x16x32_bf16 v[122:125], v[174:177], v[204:207], v[122:125]
	v_mfma_f32_16x16x32_bf16 v[110:113], v[166:169], v[212:215], v[110:113]
	v_mfma_f32_16x16x32_bf16 v[106:109], v[174:177], v[212:215], v[106:109]
	v_mfma_f32_16x16x32_bf16 v[94:97], v[166:169], v[220:223], v[94:97]
	v_mfma_f32_16x16x32_bf16 v[90:93], v[174:177], v[220:223], v[90:93]
	v_mfma_f32_16x16x32_bf16 v[78:81], v[166:169], v[228:231], v[78:81]
	v_mfma_f32_16x16x32_bf16 v[74:77], v[174:177], v[228:231], v[74:77]
	v_mfma_f32_16x16x32_bf16 v[118:121], v[178:181], v[200:203], v[118:121]
	v_mfma_f32_16x16x32_bf16 v[114:117], v[186:189], v[200:203], v[114:117]
	v_mfma_f32_16x16x32_bf16 v[102:105], v[178:181], v[208:211], v[102:105]
	v_mfma_f32_16x16x32_bf16 v[98:101], v[186:189], v[208:211], v[98:101]
	v_mfma_f32_16x16x32_bf16 v[86:89], v[178:181], v[216:219], v[86:89]
	v_mfma_f32_16x16x32_bf16 v[82:85], v[186:189], v[216:219], v[82:85]
	v_mfma_f32_16x16x32_bf16 v[70:73], v[178:181], v[224:227], v[70:73]
	v_mfma_f32_16x16x32_bf16 v[66:69], v[186:189], v[224:227], v[66:69]
	v_mfma_f32_16x16x32_bf16 v[118:121], v[182:185], v[204:207], v[118:121]
	v_mfma_f32_16x16x32_bf16 v[114:117], v[190:193], v[204:207], v[114:117]
	v_mfma_f32_16x16x32_bf16 v[102:105], v[182:185], v[212:215], v[102:105]
	v_mfma_f32_16x16x32_bf16 v[98:101], v[190:193], v[212:215], v[98:101]
	v_mfma_f32_16x16x32_bf16 v[86:89], v[182:185], v[220:223], v[86:89]
	v_mfma_f32_16x16x32_bf16 v[82:85], v[190:193], v[220:223], v[82:85]
	v_mfma_f32_16x16x32_bf16 v[70:73], v[182:185], v[228:231], v[70:73]
	v_mfma_f32_16x16x32_bf16 v[66:69], v[190:193], v[228:231], v[66:69]
	s_barrier
	s_add_i32 s38, s70, s52
	s_add_i32 m0, s38, 0xffffff80
	ds_read_b128 v[200:203], v151 offset:49152
	ds_read_b128 v[204:207], v151 offset:50176
	ds_read_b128 v[208:211], v151 offset:51200
	ds_read_b128 v[212:215], v151 offset:52224
	ds_read_b128 v[216:219], v151 offset:53248
	ds_read_b128 v[220:223], v151 offset:54272
	ds_read_b128 v[224:227], v151 offset:55296
	ds_read_b128 v[228:231], v151 offset:56320
	global_load_lds_dwordx4 v158, s[36:37] offset:128
	s_add_i32 m0, s38, 0x1f80
	s_add_i32 s38, s71, s52
	global_load_lds_dwordx4 v134, s[36:37] offset:128
	s_add_u32 s36, s36, 0x80080
	s_addc_u32 s37, s37, 0
	s_mov_b32 m0, s38
	s_nop 0
	global_load_lds_dwordx4 v158, s[36:37]
	s_add_i32 m0, s38, 0x2000
	s_nop 0
	global_load_lds_dwordx4 v134, s[36:37]
	s_waitcnt vmcnt(6) lgkmcnt(0)
	s_barrier
	v_mfma_f32_16x16x32_bf16 v[62:65], v[152:155], v[200:203], v[62:65]
	v_mfma_f32_16x16x32_bf16 v[58:61], v[170:173], v[200:203], v[58:61]
	v_mfma_f32_16x16x32_bf16 v[46:49], v[152:155], v[208:211], v[46:49]
	v_mfma_f32_16x16x32_bf16 v[42:45], v[170:173], v[208:211], v[42:45]
	v_mfma_f32_16x16x32_bf16 v[30:33], v[152:155], v[216:219], v[30:33]
	v_mfma_f32_16x16x32_bf16 v[26:29], v[170:173], v[216:219], v[26:29]
	v_mfma_f32_16x16x32_bf16 v[14:17], v[152:155], v[224:227], v[14:17]
	v_mfma_f32_16x16x32_bf16 v[10:13], v[170:173], v[224:227], v[10:13]
	v_mfma_f32_16x16x32_bf16 v[62:65], v[166:169], v[204:207], v[62:65]
	v_mfma_f32_16x16x32_bf16 v[58:61], v[174:177], v[204:207], v[58:61]
	v_mfma_f32_16x16x32_bf16 v[46:49], v[166:169], v[212:215], v[46:49]
	v_mfma_f32_16x16x32_bf16 v[42:45], v[174:177], v[212:215], v[42:45]
	v_mfma_f32_16x16x32_bf16 v[30:33], v[166:169], v[220:223], v[30:33]
	v_mfma_f32_16x16x32_bf16 v[26:29], v[174:177], v[220:223], v[26:29]
	v_mfma_f32_16x16x32_bf16 v[14:17], v[166:169], v[228:231], v[14:17]
	v_mfma_f32_16x16x32_bf16 v[10:13], v[174:177], v[228:231], v[10:13]
	v_mfma_f32_16x16x32_bf16 v[54:57], v[178:181], v[200:203], v[54:57]
	v_mfma_f32_16x16x32_bf16 v[50:53], v[186:189], v[200:203], v[50:53]
	v_mfma_f32_16x16x32_bf16 v[38:41], v[178:181], v[208:211], v[38:41]
	v_mfma_f32_16x16x32_bf16 v[34:37], v[186:189], v[208:211], v[34:37]
	v_mfma_f32_16x16x32_bf16 v[22:25], v[178:181], v[216:219], v[22:25]
	v_mfma_f32_16x16x32_bf16 v[18:21], v[186:189], v[216:219], v[18:21]
	v_mfma_f32_16x16x32_bf16 v[6:9], v[178:181], v[224:227], v[6:9]
	v_mfma_f32_16x16x32_bf16 v[2:5], v[186:189], v[224:227], v[2:5]
	v_mfma_f32_16x16x32_bf16 v[54:57], v[182:185], v[204:207], v[54:57]
	v_mfma_f32_16x16x32_bf16 v[50:53], v[190:193], v[204:207], v[50:53]
	v_mfma_f32_16x16x32_bf16 v[38:41], v[182:185], v[212:215], v[38:41]
	v_mfma_f32_16x16x32_bf16 v[34:37], v[190:193], v[212:215], v[34:37]
	v_mfma_f32_16x16x32_bf16 v[22:25], v[182:185], v[220:223], v[22:25]
	v_mfma_f32_16x16x32_bf16 v[18:21], v[190:193], v[220:223], v[18:21]
	v_mfma_f32_16x16x32_bf16 v[6:9], v[182:185], v[228:231], v[6:9]
	v_mfma_f32_16x16x32_bf16 v[2:5], v[190:193], v[228:231], v[2:5]
	s_barrier
	s_add_i32 s69, s69, 2
	s_add_u32 s30, s30, 0x100
	s_addc_u32 s31, s31, 0
	s_add_u32 s67, s67, 0x100
	s_addc_u32 s68, s68, 0
	s_cmp_gt_u32 s69, 29
	s_cbranch_scc0 .LBB0_139
	s_and_b64 vcc, exec, s[16:17]
	s_cbranch_vccz .LBB0_142
	s_barrier

; #define PG8_STAGE(bufoff, gbase, voff) do { _Pragma("unroll") for (int _i = 0; _i < 2; ++_i) \
;         __builtin_amdgcn_global_load_lds((const unsigned*)((const char*)(gbase) + (voff)[_i]), (PG8_LAS unsigned*)(lds + (bufoff) + ldsw + _i * 8192), 16, 0, 0); } while (0)
; #define PG8_LDA(dst, b, h) do { _Pragma("unroll") for (int m = 0; m < 4; ++m) _Pragma("unroll") for (int k = 0; k < 2; ++k) dst[m][k] = *(const PG8_LAS bf16x8*)(lds + PG8_SA(b, h) + aoff + m * 2048 + k * 1024); } while (0)
; #define PG8_LDB(dst, b, h) do { _Pragma("unroll") for (int n = 0; n < 2; ++n) _Pragma("unroll") for (int k = 0; k < 2; ++k) dst[n][k] = *(const PG8_LAS bf16x8*)(lds + PG8_SB(b, h) + boff + n * 2048 + k * 1024); } while (0)
; #define PG8_MMA(ai, bj, At, Bt) do { __builtin_amdgcn_s_setprio(1); _Pragma("unroll") for (int m = 0; m < 4; ++m) _Pragma("unroll") for (int n = 0; n < 2; ++n) _Pragma("unroll") for (int k = 0; k < 2; ++k) \
;         acc[ai][bj][m][n] = __builtin_amdgcn_mfma_f32_16x16x32_bf16(Bt[n][k], At[m][k], acc[ai][bj][m][n], 0, 0, 0); __builtin_amdgcn_s_setprio(0); } while (0)
; #define PG8_WAIT_V(n) asm volatile("s_waitcnt vmcnt(" #n ")" ::: "memory")
; #define PG8_WAIT_L(n) asm volatile("s_waitcnt lgkmcnt(" #n ")" ::: "memory")
; template <class Epi, class Sched, bool ALIGN_EPI = false, bool SP2 = false>
; __device__ __forceinline__ void gemm_phase(PG8_LAS unsigned char* lds, const Gemm g, const Sched& S, const Epi& E) {
;     ...
;             const bool last = (t == nt - 2);
;             const char* a1 = cA + (size_t)(t + 1) * kstep;
;             const char* a2 = last ? nA : cA + (size_t)(t + 2) * kstep; const char* b2 = last ? nB : cB + (size_t)(t + 2) * kstep;
;             const char* a3 = a2 + kstep; const char* b3 = b2 + kstep;
;             if (last && has_next) S.a_ready(nxt);
;             if constexpr (SP2) {
;             PG8_LDB(B0, 0, 0); PG8_LDB(B1, 0, 1); PG8_SCHED; PG8_LDA(At, 0, 0); PG8_STAGE(PG8_SA(1, 1), a1 + hstep, voffA);
;             PG8_WAIT_V(8); PG8_WAIT_L(0); PG8_BAR; PG8_MMA(0, 0, At, B0); PG8_MMA(0, 1, At, B1); PG8_BAR; PG8_SCHED;
;             PG8_LDA(At, 0, 1); PG8_STAGE(PG8_SB(0, 0), b2, voffB); PG8_STAGE(PG8_SB(0, 1), b2 + hstep, voffB); PG8_STAGE(PG8_SA(0, 0), a2, voffA);
;             PG8_WAIT_V(8); PG8_WAIT_L(0); PG8_BAR; PG8_MMA(1, 0, At, B0); PG8_MMA(1, 1, At, B1); PG8_BAR; PG8_SCHED;
.LBB0_667:
	s_add_u32 s30, s0, 0xfff80080
	s_addc_u32 s31, s1, -1
	s_add_i32 s66, 0, 0x10000
	s_cmp_eq_u32 s63, 28
	s_cselect_b32 s37, s23, s31
	s_cselect_b32 s36, s59, s30
	s_cselect_b32 s31, s19, s62
	s_cselect_b32 s30, s60, s61
	s_add_i32 s68, 0, 0x14000
	ds_read_b128 v[130:133], v244
	ds_read_b128 v[134:137], v244 offset:1024
	ds_read_b128 v[138:141], v244 offset:2048
	ds_read_b128 v[142:145], v244 offset:3072
	ds_read_b128 v[146:149], v245
	ds_read_b128 v[150:153], v245 offset:1024
	ds_read_b128 v[154:157], v245 offset:2048
	ds_read_b128 v[162:165], v245 offset:3072
	s_add_u32 s98, s0, 0xfff80000
	s_addc_u32 s99, s1, -1
	s_mov_b32 m0, s54
	s_nop 0
	global_load_lds_dwordx4 v172, s[98:99]
	s_mov_b32 m0, s55
	s_nop 0
	global_load_lds_dwordx4 v174, s[98:99]
	s_add_i32 m0, s48, 0xc000
	ds_read_b128 v[176:179], v201
	ds_read_b128 v[180:183], v201 offset:1024
	ds_read_b128 v[184:187], v201 offset:2048
	ds_read_b128 v[188:191], v201 offset:3072
	ds_read_b128 v[202:205], v201 offset:4096
	ds_read_b128 v[206:209], v201 offset:5120
	ds_read_b128 v[210:213], v201 offset:6144
	ds_read_b128 v[214:217], v201 offset:7168
	global_load_lds_dwordx4 v172, s[0:1]
	s_add_i32 m0, s48, 0xe000
	s_nop 0
	global_load_lds_dwordx4 v174, s[0:1]
	s_waitcnt vmcnt(8) lgkmcnt(0)
	s_barrier
	v_mfma_f32_16x16x32_bf16 v[126:129], v[130:133], v[176:179], v[126:129]
	v_mfma_f32_16x16x32_bf16 v[122:125], v[138:141], v[176:179], v[122:125]
	v_mfma_f32_16x16x32_bf16 v[110:113], v[130:133], v[184:187], v[110:113]
	v_mfma_f32_16x16x32_bf16 v[106:109], v[138:141], v[184:187], v[106:109]
	v_mfma_f32_16x16x32_bf16 v[94:97], v[130:133], v[202:205], v[94:97]
	v_mfma_f32_16x16x32_bf16 v[90:93], v[138:141], v[202:205], v[90:93]
	v_mfma_f32_16x16x32_bf16 v[78:81], v[130:133], v[210:213], v[78:81]
	v_mfma_f32_16x16x32_bf16 v[74:77], v[138:141], v[210:213], v[74:77]
	v_mfma_f32_16x16x32_bf16 v[126:129], v[134:137], v[180:183], v[126:129]
	v_mfma_f32_16x16x32_bf16 v[122:125], v[142:145], v[180:183], v[122:125]
	v_mfma_f32_16x16x32_bf16 v[110:113], v[134:137], v[188:191], v[110:113]
	v_mfma_f32_16x16x32_bf16 v[106:109], v[142:145], v[188:191], v[106:109]
	v_mfma_f32_16x16x32_bf16 v[94:97], v[134:137], v[206:209], v[94:97]
	v_mfma_f32_16x16x32_bf16 v[90:93], v[142:145], v[206:209], v[90:93]
	v_mfma_f32_16x16x32_bf16 v[78:81], v[134:137], v[214:217], v[78:81]
	v_mfma_f32_16x16x32_bf16 v[74:77], v[142:145], v[214:217], v[74:77]
	v_mfma_f32_16x16x32_bf16 v[118:121], v[146:149], v[176:179], v[118:121]
	v_mfma_f32_16x16x32_bf16 v[114:117], v[154:157], v[176:179], v[114:117]
	v_mfma_f32_16x16x32_bf16 v[102:105], v[146:149], v[184:187], v[102:105]
	v_mfma_f32_16x16x32_bf16 v[98:101], v[154:157], v[184:187], v[98:101]
	v_mfma_f32_16x16x32_bf16 v[86:89], v[146:149], v[202:205], v[86:89]
	v_mfma_f32_16x16x32_bf16 v[82:85], v[154:157], v[202:205], v[82:85]
	v_mfma_f32_16x16x32_bf16 v[70:73], v[146:149], v[210:213], v[70:73]
	v_mfma_f32_16x16x32_bf16 v[66:69], v[154:157], v[210:213], v[66:69]
	v_mfma_f32_16x16x32_bf16 v[118:121], v[150:153], v[180:183], v[118:121]
	v_mfma_f32_16x16x32_bf16 v[114:117], v[162:165], v[180:183], v[114:117]
	v_mfma_f32_16x16x32_bf16 v[102:105], v[150:153], v[188:191], v[102:105]
	v_mfma_f32_16x16x32_bf16 v[98:101], v[162:165], v[188:191], v[98:101]
	v_mfma_f32_16x16x32_bf16 v[86:89], v[150:153], v[206:209], v[86:89]
	v_mfma_f32_16x16x32_bf16 v[82:85], v[162:165], v[206:209], v[82:85]
	v_mfma_f32_16x16x32_bf16 v[70:73], v[150:153], v[214:217], v[70:73]
	v_mfma_f32_16x16x32_bf16 v[66:69], v[162:165], v[214:217], v[66:69]
	s_barrier
	s_add_i32 s66, s66, s47
	s_mov_b32 m0, s66
	ds_read_b128 v[176:179], v201 offset:16384
	ds_read_b128 v[180:183], v201 offset:17408
	ds_read_b128 v[184:187], v201 offset:18432
	ds_read_b128 v[188:191], v201 offset:19456
	ds_read_b128 v[202:205], v201 offset:20480
	ds_read_b128 v[206:209], v201 offset:21504
	ds_read_b128 v[210:213], v201 offset:22528
	ds_read_b128 v[214:217], v201 offset:23552
	global_load_lds_dwordx4 v158, s[30:31]
	s_add_i32 m0, s66, 0x2000
	s_add_u32 s66, s30, 0x80000
	s_addc_u32 s67, s31, 0
	s_add_i32 s68, s68, s47
	global_load_lds_dwordx4 v166, s[30:31]
	s_mov_b32 m0, s68
	s_nop 0
	global_load_lds_dwordx4 v158, s[66:67]
	s_add_i32 m0, s68, 0x2000
	s_nop 0
	global_load_lds_dwordx4 v166, s[66:67]
	s_waitcnt vmcnt(6) lgkmcnt(0)
	s_barrier
	v_mfma_f32_16x16x32_bf16 v[62:65], v[130:133], v[176:179], v[62:65]
	v_mfma_f32_16x16x32_bf16 v[58:61], v[138:141], v[176:179], v[58:61]
	v_mfma_f32_16x16x32_bf16 v[46:49], v[130:133], v[184:187], v[46:49]
	v_mfma_f32_16x16x32_bf16 v[42:45], v[138:141], v[184:187], v[42:45]
	v_mfma_f32_16x16x32_bf16 v[30:33], v[130:133], v[202:205], v[30:33]
	v_mfma_f32_16x16x32_bf16 v[26:29], v[138:141], v[202:205], v[26:29]
	v_mfma_f32_16x16x32_bf16 v[14:17], v[130:133], v[210:213], v[14:17]
	v_mfma_f32_16x16x32_bf16 v[10:13], v[138:141], v[210:213], v[10:13]
	v_mfma_f32_16x16x32_bf16 v[62:65], v[134:137], v[180:183], v[62:65]
	v_mfma_f32_16x16x32_bf16 v[58:61], v[142:145], v[180:183], v[58:61]
	v_mfma_f32_16x16x32_bf16 v[46:49], v[134:137], v[188:191], v[46:49]
	v_mfma_f32_16x16x32_bf16 v[42:45], v[142:145], v[188:191], v[42:45]
	v_mfma_f32_16x16x32_bf16 v[30:33], v[134:137], v[206:209], v[30:33]
	v_mfma_f32_16x16x32_bf16 v[26:29], v[142:145], v[206:209], v[26:29]
	v_mfma_f32_16x16x32_bf16 v[14:17], v[134:137], v[214:217], v[14:17]
	v_mfma_f32_16x16x32_bf16 v[10:13], v[142:145], v[214:217], v[10:13]
	v_mfma_f32_16x16x32_bf16 v[54:57], v[146:149], v[176:179], v[54:57]
	v_mfma_f32_16x16x32_bf16 v[50:53], v[154:157], v[176:179], v[50:53]
	v_mfma_f32_16x16x32_bf16 v[38:41], v[146:149], v[184:187], v[38:41]
	v_mfma_f32_16x16x32_bf16 v[34:37], v[154:157], v[184:187], v[34:37]
	v_mfma_f32_16x16x32_bf16 v[22:25], v[146:149], v[202:205], v[22:25]
	v_mfma_f32_16x16x32_bf16 v[18:21], v[154:157], v[202:205], v[18:21]
	v_mfma_f32_16x16x32_bf16 v[6:9], v[146:149], v[210:213], v[6:9]
	v_mfma_f32_16x16x32_bf16 v[2:5], v[154:157], v[210:213], v[2:5]
	v_mfma_f32_16x16x32_bf16 v[54:57], v[150:153], v[180:183], v[54:57]
	v_mfma_f32_16x16x32_bf16 v[50:53], v[162:165], v[180:183], v[50:53]
	v_mfma_f32_16x16x32_bf16 v[38:41], v[150:153], v[188:191], v[38:41]
	v_mfma_f32_16x16x32_bf16 v[34:37], v[162:165], v[188:191], v[34:37]
	v_mfma_f32_16x16x32_bf16 v[22:25], v[150:153], v[206:209], v[22:25]
	v_mfma_f32_16x16x32_bf16 v[18:21], v[162:165], v[206:209], v[18:21]
	v_mfma_f32_16x16x32_bf16 v[6:9], v[150:153], v[214:217], v[6:9]
	v_mfma_f32_16x16x32_bf16 v[2:5], v[162:165], v[214:217], v[2:5]
	s_barrier
; #define PG8_STAGE(bufoff, gbase, voff) do { _Pragma("unroll") for (int _i = 0; _i < 2; ++_i) \
;         __builtin_amdgcn_global_load_lds((const unsigned*)((const char*)(gbase) + (voff)[_i]), (PG8_LAS unsigned*)(lds + (bufoff) + ldsw + _i * 8192), 16, 0, 0); } while (0)
; #define PG8_LDA(dst, b, h) do { _Pragma("unroll") for (int m = 0; m < 4; ++m) _Pragma("unroll") for (int k = 0; k < 2; ++k) dst[m][k] = *(const PG8_LAS bf16x8*)(lds + PG8_SA(b, h) + aoff + m * 2048 + k * 1024); } while (0)
; #define PG8_WAIT_V(n) asm volatile("s_waitcnt vmcnt(" #n ")" ::: "memory")
; #define PG8_WAIT_L(n) asm volatile("s_waitcnt lgkmcnt(" #n ")" ::: "memory")
; template <class Epi, class Sched, bool ALIGN_EPI = false, bool SP2 = false>
; __device__ __forceinline__ void gemm_phase(PG8_LAS unsigned char* lds, const Gemm g, const Sched& S, const Epi& E) {
;     ...
;         for (int t = 0; t < nt; t += 2) {
;             const bool last = (t == nt - 2);
;             const char* a1 = cA + (size_t)(t + 1) * kstep;
;             const char* a2 = last ? nA : cA + (size_t)(t + 2) * kstep; const char* b2 = last ? nB : cB + (size_t)(t + 2) * kstep;
;             const char* a3 = a2 + kstep; const char* b3 = b2 + kstep;
;             if (last && has_next) S.a_ready(nxt);
;             if constexpr (SP2) {
;             PG8_LDB(B0, 0, 0); PG8_LDB(B1, 0, 1); PG8_SCHED; PG8_LDA(At, 0, 0); PG8_STAGE(PG8_SA(1, 1), a1 + hstep, voffA);
;             PG8_WAIT_V(8); PG8_WAIT_L(0); PG8_BAR; PG8_MMA(0, 0, At, B0); PG8_MMA(0, 1, At, B1); PG8_BAR; PG8_SCHED;
;             PG8_LDA(At, 0, 1); PG8_STAGE(PG8_SB(0, 0), b2, voffB); PG8_STAGE(PG8_SB(0, 1), b2 + hstep, voffB); PG8_STAGE(PG8_SA(0, 0), a2, voffA);
;             PG8_WAIT_V(8); PG8_WAIT_L(0); PG8_BAR; PG8_MMA(1, 0, At, B0); PG8_MMA(1, 1, At, B1); PG8_BAR; PG8_SCHED;
;             PG8_LDB(B0, 1, 0); PG8_LDB(B1, 1, 1); PG8_SCHED; PG8_LDA(At, 1, 0); PG8_STAGE(PG8_SA(0, 1), a2 + hstep, voffA);
;             PG8_WAIT_V(8); PG8_WAIT_L(0); PG8_BAR; PG8_MMA(0, 0, At, B0); PG8_MMA(0, 1, At, B1); PG8_BAR; PG8_SCHED;
;             PG8_LDA(At, 1, 1); PG8_STAGE(PG8_SB(1, 0), b3, voffB); PG8_STAGE(PG8_SB(1, 1), b3 + hstep, voffB); PG8_STAGE(PG8_SA(1, 0), a3, voffA);
;             PG8_WAIT_V(8); PG8_WAIT_L(0); PG8_BAR; PG8_MMA(1, 0, At, B0); PG8_MMA(1, 1, At, B1); PG8_BAR; PG8_SCHED;
;     ...
;         if constexpr (ALIGN_EPI) { if (wr == 0) PG8_BAR; }
	s_add_i32 s66, 0, 0x18000
	s_add_i32 s67, 0, 0x1c000
	ds_read_b128 v[130:133], v246
	ds_read_b128 v[134:137], v246 offset:1024
	ds_read_b128 v[138:141], v246 offset:2048
	ds_read_b128 v[142:145], v246 offset:3072
	ds_read_b128 v[146:149], v247
	ds_read_b128 v[150:153], v247 offset:1024
	ds_read_b128 v[154:157], v247 offset:2048
	ds_read_b128 v[162:165], v247 offset:3072
	s_mov_b32 m0, s48
	s_nop 0
	global_load_lds_dwordx4 v170, s[36:37]
	s_mov_b32 m0, s49
	s_nop 0
	global_load_lds_dwordx4 v168, s[36:37]
	s_add_u32 s36, s36, 0x80000
	s_addc_u32 s37, s37, 0
	s_mov_b32 m0, s50
	ds_read_b128 v[176:179], v201 offset:32768
	ds_read_b128 v[180:183], v201 offset:33792
	ds_read_b128 v[184:187], v201 offset:34816
	ds_read_b128 v[188:191], v201 offset:35840
	ds_read_b128 v[202:205], v201 offset:36864
	ds_read_b128 v[206:209], v201 offset:37888
	ds_read_b128 v[210:213], v201 offset:38912
	ds_read_b128 v[214:217], v201 offset:39936
	global_load_lds_dwordx4 v170, s[36:37]
	s_mov_b32 m0, s51
	s_nop 0
	global_load_lds_dwordx4 v168, s[36:37]
	s_waitcnt vmcnt(8) lgkmcnt(0)
	s_barrier
	v_mfma_f32_16x16x32_bf16 v[126:129], v[130:133], v[176:179], v[126:129]
	v_mfma_f32_16x16x32_bf16 v[122:125], v[138:141], v[176:179], v[122:125]
	v_mfma_f32_16x16x32_bf16 v[110:113], v[130:133], v[184:187], v[110:113]
	v_mfma_f32_16x16x32_bf16 v[106:109], v[138:141], v[184:187], v[106:109]
	v_mfma_f32_16x16x32_bf16 v[94:97], v[130:133], v[202:205], v[94:97]
	v_mfma_f32_16x16x32_bf16 v[90:93], v[138:141], v[202:205], v[90:93]
	v_mfma_f32_16x16x32_bf16 v[78:81], v[130:133], v[210:213], v[78:81]
	v_mfma_f32_16x16x32_bf16 v[74:77], v[138:141], v[210:213], v[74:77]
	v_mfma_f32_16x16x32_bf16 v[126:129], v[134:137], v[180:183], v[126:129]
	v_mfma_f32_16x16x32_bf16 v[122:125], v[142:145], v[180:183], v[122:125]
	v_mfma_f32_16x16x32_bf16 v[110:113], v[134:137], v[188:191], v[110:113]
	v_mfma_f32_16x16x32_bf16 v[106:109], v[142:145], v[188:191], v[106:109]
	v_mfma_f32_16x16x32_bf16 v[94:97], v[134:137], v[206:209], v[94:97]
	v_mfma_f32_16x16x32_bf16 v[90:93], v[142:145], v[206:209], v[90:93]
	v_mfma_f32_16x16x32_bf16 v[78:81], v[134:137], v[214:217], v[78:81]
	v_mfma_f32_16x16x32_bf16 v[74:77], v[142:145], v[214:217], v[74:77]
	v_mfma_f32_16x16x32_bf16 v[118:121], v[146:149], v[176:179], v[118:121]
	v_mfma_f32_16x16x32_bf16 v[114:117], v[154:157], v[176:179], v[114:117]
	v_mfma_f32_16x16x32_bf16 v[102:105], v[146:149], v[184:187], v[102:105]
	v_mfma_f32_16x16x32_bf16 v[98:101], v[154:157], v[184:187], v[98:101]
	v_mfma_f32_16x16x32_bf16 v[86:89], v[146:149], v[202:205], v[86:89]
	v_mfma_f32_16x16x32_bf16 v[82:85], v[154:157], v[202:205], v[82:85]
	v_mfma_f32_16x16x32_bf16 v[70:73], v[146:149], v[210:213], v[70:73]
	v_mfma_f32_16x16x32_bf16 v[66:69], v[154:157], v[210:213], v[66:69]
	v_mfma_f32_16x16x32_bf16 v[118:121], v[150:153], v[180:183], v[118:121]
	v_mfma_f32_16x16x32_bf16 v[114:117], v[162:165], v[180:183], v[114:117]
	v_mfma_f32_16x16x32_bf16 v[102:105], v[150:153], v[188:191], v[102:105]
	v_mfma_f32_16x16x32_bf16 v[98:101], v[162:165], v[188:191], v[98:101]
	v_mfma_f32_16x16x32_bf16 v[86:89], v[150:153], v[206:209], v[86:89]
	v_mfma_f32_16x16x32_bf16 v[82:85], v[162:165], v[206:209], v[82:85]
	v_mfma_f32_16x16x32_bf16 v[70:73], v[150:153], v[214:217], v[70:73]
	v_mfma_f32_16x16x32_bf16 v[66:69], v[162:165], v[214:217], v[66:69]
	s_barrier
	s_add_i32 s36, s66, s47
	s_add_i32 m0, s36, 0xffffff80
	ds_read_b128 v[176:179], v201 offset:49152
	ds_read_b128 v[180:183], v201 offset:50176
	ds_read_b128 v[184:187], v201 offset:51200
	ds_read_b128 v[188:191], v201 offset:52224
	ds_read_b128 v[202:205], v201 offset:53248
	ds_read_b128 v[206:209], v201 offset:54272
	ds_read_b128 v[210:213], v201 offset:55296
	ds_read_b128 v[214:217], v201 offset:56320
	global_load_lds_dwordx4 v158, s[30:31] offset:128
	s_add_i32 m0, s36, 0x1f80
	s_add_i32 s36, s67, s47
	global_load_lds_dwordx4 v166, s[30:31] offset:128
	s_add_u32 s30, s30, 0x80080
	s_addc_u32 s31, s31, 0
	s_mov_b32 m0, s36
	s_nop 0
	global_load_lds_dwordx4 v158, s[30:31]
	s_add_i32 m0, s36, 0x2000
	s_nop 0
	global_load_lds_dwordx4 v166, s[30:31]
	s_waitcnt vmcnt(6) lgkmcnt(0)
	s_barrier
	v_mfma_f32_16x16x32_bf16 v[62:65], v[130:133], v[176:179], v[62:65]
	v_mfma_f32_16x16x32_bf16 v[58:61], v[138:141], v[176:179], v[58:61]
	v_mfma_f32_16x16x32_bf16 v[46:49], v[130:133], v[184:187], v[46:49]
	v_mfma_f32_16x16x32_bf16 v[42:45], v[138:141], v[184:187], v[42:45]
	v_mfma_f32_16x16x32_bf16 v[30:33], v[130:133], v[202:205], v[30:33]
	v_mfma_f32_16x16x32_bf16 v[26:29], v[138:141], v[202:205], v[26:29]
	v_mfma_f32_16x16x32_bf16 v[14:17], v[130:133], v[210:213], v[14:17]
	v_mfma_f32_16x16x32_bf16 v[10:13], v[138:141], v[210:213], v[10:13]
	v_mfma_f32_16x16x32_bf16 v[62:65], v[134:137], v[180:183], v[62:65]
	v_mfma_f32_16x16x32_bf16 v[58:61], v[142:145], v[180:183], v[58:61]
	v_mfma_f32_16x16x32_bf16 v[46:49], v[134:137], v[188:191], v[46:49]
	v_mfma_f32_16x16x32_bf16 v[42:45], v[142:145], v[188:191], v[42:45]
	v_mfma_f32_16x16x32_bf16 v[30:33], v[134:137], v[206:209], v[30:33]
	v_mfma_f32_16x16x32_bf16 v[26:29], v[142:145], v[206:209], v[26:29]
	v_mfma_f32_16x16x32_bf16 v[14:17], v[134:137], v[214:217], v[14:17]
	v_mfma_f32_16x16x32_bf16 v[10:13], v[142:145], v[214:217], v[10:13]
	v_mfma_f32_16x16x32_bf16 v[54:57], v[146:149], v[176:179], v[54:57]
	v_mfma_f32_16x16x32_bf16 v[50:53], v[154:157], v[176:179], v[50:53]
	v_mfma_f32_16x16x32_bf16 v[38:41], v[146:149], v[184:187], v[38:41]
	v_mfma_f32_16x16x32_bf16 v[34:37], v[154:157], v[184:187], v[34:37]
	v_mfma_f32_16x16x32_bf16 v[22:25], v[146:149], v[202:205], v[22:25]
	v_mfma_f32_16x16x32_bf16 v[18:21], v[154:157], v[202:205], v[18:21]
	v_mfma_f32_16x16x32_bf16 v[6:9], v[146:149], v[210:213], v[6:9]
	v_mfma_f32_16x16x32_bf16 v[2:5], v[154:157], v[210:213], v[2:5]
	v_mfma_f32_16x16x32_bf16 v[54:57], v[150:153], v[180:183], v[54:57]
	v_mfma_f32_16x16x32_bf16 v[50:53], v[162:165], v[180:183], v[50:53]
	v_mfma_f32_16x16x32_bf16 v[38:41], v[150:153], v[188:191], v[38:41]
	v_mfma_f32_16x16x32_bf16 v[34:37], v[162:165], v[188:191], v[34:37]
	v_mfma_f32_16x16x32_bf16 v[22:25], v[150:153], v[206:209], v[22:25]
	v_mfma_f32_16x16x32_bf16 v[18:21], v[162:165], v[206:209], v[18:21]
	v_mfma_f32_16x16x32_bf16 v[6:9], v[150:153], v[214:217], v[6:9]
	v_mfma_f32_16x16x32_bf16 v[2:5], v[162:165], v[214:217], v[2:5]
	s_barrier
	s_add_i32 s63, s63, 2
	s_add_u32 s0, s0, 0x100
	s_addc_u32 s1, s1, 0
	s_add_u32 s61, s61, 0x100
	s_addc_u32 s62, s62, 0
	s_cmp_gt_u32 s63, 29
	s_cbranch_scc0 .LBB0_667
	s_and_b64 vcc, exec, s[16:17]
	s_cbranch_vccz .LBB0_670
	s_barrier

; #define PG8_STAGE(bufoff, gbase, voff) do { _Pragma("unroll") for (int _i = 0; _i < 2; ++_i) \
;         __builtin_amdgcn_global_load_lds((const unsigned*)((const char*)(gbase) + (voff)[_i]), (PG8_LAS unsigned*)(lds + (bufoff) + ldsw + _i * 8192), 16, 0, 0); } while (0)
; #define PG8_LDA(dst, b, h) do { _Pragma("unroll") for (int m = 0; m < 4; ++m) _Pragma("unroll") for (int k = 0; k < 2; ++k) dst[m][k] = *(const PG8_LAS bf16x8*)(lds + PG8_SA(b, h) + aoff + m * 2048 + k * 1024); } while (0)
; #define PG8_LDB(dst, b, h) do { _Pragma("unroll") for (int n = 0; n < 2; ++n) _Pragma("unroll") for (int k = 0; k < 2; ++k) dst[n][k] = *(const PG8_LAS bf16x8*)(lds + PG8_SB(b, h) + boff + n * 2048 + k * 1024); } while (0)
; #define PG8_MMA(ai, bj, At, Bt) do { __builtin_amdgcn_s_setprio(1); _Pragma("unroll") for (int m = 0; m < 4; ++m) _Pragma("unroll") for (int n = 0; n < 2; ++n) _Pragma("unroll") for (int k = 0; k < 2; ++k) \
;         acc[ai][bj][m][n] = __builtin_amdgcn_mfma_f32_16x16x32_bf16(Bt[n][k], At[m][k], acc[ai][bj][m][n], 0, 0, 0); __builtin_amdgcn_s_setprio(0); } while (0)
; #define PG8_WAIT_V(n) asm volatile("s_waitcnt vmcnt(" #n ")" ::: "memory")
; #define PG8_WAIT_L(n) asm volatile("s_waitcnt lgkmcnt(" #n ")" ::: "memory")
; template <class Epi, class Sched, bool ALIGN_EPI = false, bool SP2 = false>
; __device__ __forceinline__ void gemm_phase(PG8_LAS unsigned char* lds, const Gemm g, const Sched& S, const Epi& E) {
;     ...
;             const bool last = (t == nt - 2);
;             const char* a1 = cA + (size_t)(t + 1) * kstep;
;             const char* a2 = last ? nA : cA + (size_t)(t + 2) * kstep; const char* b2 = last ? nB : cB + (size_t)(t + 2) * kstep;
;             const char* a3 = a2 + kstep; const char* b3 = b2 + kstep;
;             if (last && has_next) S.a_ready(nxt);
;             if constexpr (SP2) {
;             PG8_LDB(B0, 0, 0); PG8_LDB(B1, 0, 1); PG8_SCHED; PG8_LDA(At, 0, 0); PG8_STAGE(PG8_SA(1, 1), a1 + hstep, voffA);
;             PG8_WAIT_V(8); PG8_WAIT_L(0); PG8_BAR; PG8_MMA(0, 0, At, B0); PG8_MMA(0, 1, At, B1); PG8_BAR; PG8_SCHED;
;             PG8_LDA(At, 0, 1); PG8_STAGE(PG8_SB(0, 0), b2, voffB); PG8_STAGE(PG8_SB(0, 1), b2 + hstep, voffB); PG8_STAGE(PG8_SA(0, 0), a2, voffA);
;             PG8_WAIT_V(8); PG8_WAIT_L(0); PG8_BAR; PG8_MMA(1, 0, At, B0); PG8_MMA(1, 1, At, B1); PG8_BAR; PG8_SCHED;
.LBB0_762:
	s_add_u32 s30, s0, 0xfff80080
	s_addc_u32 s31, s1, -1
	s_add_i32 s67, 0, 0x10000
	s_cmp_eq_u32 s66, 28
	s_cselect_b32 s37, s23, s31
	s_cselect_b32 s36, s60, s30
	s_cselect_b32 s31, s19, s63
	s_cselect_b32 s30, s61, s62
	s_add_i32 s70, 0, 0x14000
	ds_read_b128 v[140:143], v244
	ds_read_b128 v[152:155], v244 offset:1024
	ds_read_b128 v[162:165], v244 offset:2048
	ds_read_b128 v[166:169], v244 offset:3072
	ds_read_b128 v[170:173], v245
	ds_read_b128 v[174:177], v245 offset:1024
	ds_read_b128 v[178:181], v245 offset:2048
	ds_read_b128 v[182:185], v245 offset:3072
	s_add_u32 s98, s0, 0xfff80000
	s_addc_u32 s99, s1, -1
	s_mov_b32 m0, s52
	s_nop 0
	global_load_lds_dwordx4 v136, s[98:99]
	s_mov_b32 m0, s53
	s_nop 0
	global_load_lds_dwordx4 v138, s[98:99]
	s_add_i32 m0, s47, 0xc000
	ds_read_b128 v[186:189], v150
	ds_read_b128 v[190:193], v150 offset:1024
	ds_read_b128 v[200:203], v150 offset:2048
	ds_read_b128 v[204:207], v150 offset:3072
	ds_read_b128 v[208:211], v150 offset:4096
	ds_read_b128 v[212:215], v150 offset:5120
	ds_read_b128 v[216:219], v150 offset:6144
	ds_read_b128 v[220:223], v150 offset:7168
	global_load_lds_dwordx4 v136, s[0:1]
	s_add_i32 m0, s47, 0xe000
	s_nop 0
	global_load_lds_dwordx4 v138, s[0:1]
	s_waitcnt vmcnt(8) lgkmcnt(0)
	s_barrier
	v_mfma_f32_16x16x32_bf16 v[126:129], v[140:143], v[186:189], v[126:129]
	v_mfma_f32_16x16x32_bf16 v[122:125], v[162:165], v[186:189], v[122:125]
	v_mfma_f32_16x16x32_bf16 v[110:113], v[140:143], v[200:203], v[110:113]
	v_mfma_f32_16x16x32_bf16 v[106:109], v[162:165], v[200:203], v[106:109]
	v_mfma_f32_16x16x32_bf16 v[94:97], v[140:143], v[208:211], v[94:97]
	v_mfma_f32_16x16x32_bf16 v[90:93], v[162:165], v[208:211], v[90:93]
	v_mfma_f32_16x16x32_bf16 v[78:81], v[140:143], v[216:219], v[78:81]
	v_mfma_f32_16x16x32_bf16 v[74:77], v[162:165], v[216:219], v[74:77]
	v_mfma_f32_16x16x32_bf16 v[126:129], v[152:155], v[190:193], v[126:129]
	v_mfma_f32_16x16x32_bf16 v[122:125], v[166:169], v[190:193], v[122:125]
	v_mfma_f32_16x16x32_bf16 v[110:113], v[152:155], v[204:207], v[110:113]
	v_mfma_f32_16x16x32_bf16 v[106:109], v[166:169], v[204:207], v[106:109]
	v_mfma_f32_16x16x32_bf16 v[94:97], v[152:155], v[212:215], v[94:97]
	v_mfma_f32_16x16x32_bf16 v[90:93], v[166:169], v[212:215], v[90:93]
	v_mfma_f32_16x16x32_bf16 v[78:81], v[152:155], v[220:223], v[78:81]
	v_mfma_f32_16x16x32_bf16 v[74:77], v[166:169], v[220:223], v[74:77]
	v_mfma_f32_16x16x32_bf16 v[118:121], v[170:173], v[186:189], v[118:121]
	v_mfma_f32_16x16x32_bf16 v[114:117], v[178:181], v[186:189], v[114:117]
	v_mfma_f32_16x16x32_bf16 v[102:105], v[170:173], v[200:203], v[102:105]
	v_mfma_f32_16x16x32_bf16 v[98:101], v[178:181], v[200:203], v[98:101]
	v_mfma_f32_16x16x32_bf16 v[86:89], v[170:173], v[208:211], v[86:89]
	v_mfma_f32_16x16x32_bf16 v[82:85], v[178:181], v[208:211], v[82:85]
	v_mfma_f32_16x16x32_bf16 v[70:73], v[170:173], v[216:219], v[70:73]
	v_mfma_f32_16x16x32_bf16 v[66:69], v[178:181], v[216:219], v[66:69]
	v_mfma_f32_16x16x32_bf16 v[118:121], v[174:177], v[190:193], v[118:121]
	v_mfma_f32_16x16x32_bf16 v[114:117], v[182:185], v[190:193], v[114:117]
	v_mfma_f32_16x16x32_bf16 v[102:105], v[174:177], v[204:207], v[102:105]
	v_mfma_f32_16x16x32_bf16 v[98:101], v[182:185], v[204:207], v[98:101]
	v_mfma_f32_16x16x32_bf16 v[86:89], v[174:177], v[212:215], v[86:89]
	v_mfma_f32_16x16x32_bf16 v[82:85], v[182:185], v[212:215], v[82:85]
	v_mfma_f32_16x16x32_bf16 v[70:73], v[174:177], v[220:223], v[70:73]
	v_mfma_f32_16x16x32_bf16 v[66:69], v[182:185], v[220:223], v[66:69]
	s_barrier
	s_add_i32 s67, s67, s46
	s_mov_b32 m0, s67
	ds_read_b128 v[186:189], v150 offset:16384
	ds_read_b128 v[190:193], v150 offset:17408
	ds_read_b128 v[200:203], v150 offset:18432
	ds_read_b128 v[204:207], v150 offset:19456
	ds_read_b128 v[208:211], v150 offset:20480
	ds_read_b128 v[212:215], v150 offset:21504
	ds_read_b128 v[216:219], v150 offset:22528
	ds_read_b128 v[220:223], v150 offset:23552
	global_load_lds_dwordx4 v158, s[30:31]
	s_add_i32 m0, s67, 0x2000
	s_add_u32 s68, s30, 0x80000
	s_addc_u32 s69, s31, 0
	s_add_i32 s67, s70, s46
	global_load_lds_dwordx4 v134, s[30:31]
	s_mov_b32 m0, s67
	s_nop 0
	global_load_lds_dwordx4 v158, s[68:69]
	s_add_i32 m0, s67, 0x2000
	s_nop 0
	global_load_lds_dwordx4 v134, s[68:69]
	s_waitcnt vmcnt(6) lgkmcnt(0)
	s_barrier
	v_mfma_f32_16x16x32_bf16 v[62:65], v[140:143], v[186:189], v[62:65]
	v_mfma_f32_16x16x32_bf16 v[58:61], v[162:165], v[186:189], v[58:61]
	v_mfma_f32_16x16x32_bf16 v[46:49], v[140:143], v[200:203], v[46:49]
	v_mfma_f32_16x16x32_bf16 v[42:45], v[162:165], v[200:203], v[42:45]
	v_mfma_f32_16x16x32_bf16 v[30:33], v[140:143], v[208:211], v[30:33]
	v_mfma_f32_16x16x32_bf16 v[26:29], v[162:165], v[208:211], v[26:29]
	v_mfma_f32_16x16x32_bf16 v[14:17], v[140:143], v[216:219], v[14:17]
	v_mfma_f32_16x16x32_bf16 v[10:13], v[162:165], v[216:219], v[10:13]
	v_mfma_f32_16x16x32_bf16 v[62:65], v[152:155], v[190:193], v[62:65]
	v_mfma_f32_16x16x32_bf16 v[58:61], v[166:169], v[190:193], v[58:61]
	v_mfma_f32_16x16x32_bf16 v[46:49], v[152:155], v[204:207], v[46:49]
	v_mfma_f32_16x16x32_bf16 v[42:45], v[166:169], v[204:207], v[42:45]
	v_mfma_f32_16x16x32_bf16 v[30:33], v[152:155], v[212:215], v[30:33]
	v_mfma_f32_16x16x32_bf16 v[26:29], v[166:169], v[212:215], v[26:29]
	v_mfma_f32_16x16x32_bf16 v[14:17], v[152:155], v[220:223], v[14:17]
	v_mfma_f32_16x16x32_bf16 v[10:13], v[166:169], v[220:223], v[10:13]
	v_mfma_f32_16x16x32_bf16 v[54:57], v[170:173], v[186:189], v[54:57]
	v_mfma_f32_16x16x32_bf16 v[50:53], v[178:181], v[186:189], v[50:53]
	v_mfma_f32_16x16x32_bf16 v[38:41], v[170:173], v[200:203], v[38:41]
	v_mfma_f32_16x16x32_bf16 v[34:37], v[178:181], v[200:203], v[34:37]
	v_mfma_f32_16x16x32_bf16 v[22:25], v[170:173], v[208:211], v[22:25]
	v_mfma_f32_16x16x32_bf16 v[18:21], v[178:181], v[208:211], v[18:21]
	v_mfma_f32_16x16x32_bf16 v[6:9], v[170:173], v[216:219], v[6:9]
	v_mfma_f32_16x16x32_bf16 v[2:5], v[178:181], v[216:219], v[2:5]
	v_mfma_f32_16x16x32_bf16 v[54:57], v[174:177], v[190:193], v[54:57]
	v_mfma_f32_16x16x32_bf16 v[50:53], v[182:185], v[190:193], v[50:53]
	v_mfma_f32_16x16x32_bf16 v[38:41], v[174:177], v[204:207], v[38:41]
	v_mfma_f32_16x16x32_bf16 v[34:37], v[182:185], v[204:207], v[34:37]
	v_mfma_f32_16x16x32_bf16 v[22:25], v[174:177], v[212:215], v[22:25]
	v_mfma_f32_16x16x32_bf16 v[18:21], v[182:185], v[212:215], v[18:21]
	v_mfma_f32_16x16x32_bf16 v[6:9], v[174:177], v[220:223], v[6:9]
	v_mfma_f32_16x16x32_bf16 v[2:5], v[182:185], v[220:223], v[2:5]
	s_barrier
; #define PG8_STAGE(bufoff, gbase, voff) do { _Pragma("unroll") for (int _i = 0; _i < 2; ++_i) \
;         __builtin_amdgcn_global_load_lds((const unsigned*)((const char*)(gbase) + (voff)[_i]), (PG8_LAS unsigned*)(lds + (bufoff) + ldsw + _i * 8192), 16, 0, 0); } while (0)
; #define PG8_LDA(dst, b, h) do { _Pragma("unroll") for (int m = 0; m < 4; ++m) _Pragma("unroll") for (int k = 0; k < 2; ++k) dst[m][k] = *(const PG8_LAS bf16x8*)(lds + PG8_SA(b, h) + aoff + m * 2048 + k * 1024); } while (0)
; #define PG8_WAIT_V(n) asm volatile("s_waitcnt vmcnt(" #n ")" ::: "memory")
; #define PG8_WAIT_L(n) asm volatile("s_waitcnt lgkmcnt(" #n ")" ::: "memory")
; template <class Epi, class Sched, bool ALIGN_EPI = false, bool SP2 = false>
; __device__ __forceinline__ void gemm_phase(PG8_LAS unsigned char* lds, const Gemm g, const Sched& S, const Epi& E) {
;     ...
;         for (int t = 0; t < nt; t += 2) {
;             const bool last = (t == nt - 2);
;             const char* a1 = cA + (size_t)(t + 1) * kstep;
;             const char* a2 = last ? nA : cA + (size_t)(t + 2) * kstep; const char* b2 = last ? nB : cB + (size_t)(t + 2) * kstep;
;             const char* a3 = a2 + kstep; const char* b3 = b2 + kstep;
;             if (last && has_next) S.a_ready(nxt);
;             if constexpr (SP2) {
;             PG8_LDB(B0, 0, 0); PG8_LDB(B1, 0, 1); PG8_SCHED; PG8_LDA(At, 0, 0); PG8_STAGE(PG8_SA(1, 1), a1 + hstep, voffA);
;             PG8_WAIT_V(8); PG8_WAIT_L(0); PG8_BAR; PG8_MMA(0, 0, At, B0); PG8_MMA(0, 1, At, B1); PG8_BAR; PG8_SCHED;
;             PG8_LDA(At, 0, 1); PG8_STAGE(PG8_SB(0, 0), b2, voffB); PG8_STAGE(PG8_SB(0, 1), b2 + hstep, voffB); PG8_STAGE(PG8_SA(0, 0), a2, voffA);
;             PG8_WAIT_V(8); PG8_WAIT_L(0); PG8_BAR; PG8_MMA(1, 0, At, B0); PG8_MMA(1, 1, At, B1); PG8_BAR; PG8_SCHED;
;             PG8_LDB(B0, 1, 0); PG8_LDB(B1, 1, 1); PG8_SCHED; PG8_LDA(At, 1, 0); PG8_STAGE(PG8_SA(0, 1), a2 + hstep, voffA);
;             PG8_WAIT_V(8); PG8_WAIT_L(0); PG8_BAR; PG8_MMA(0, 0, At, B0); PG8_MMA(0, 1, At, B1); PG8_BAR; PG8_SCHED;
;             PG8_LDA(At, 1, 1); PG8_STAGE(PG8_SB(1, 0), b3, voffB); PG8_STAGE(PG8_SB(1, 1), b3 + hstep, voffB); PG8_STAGE(PG8_SA(1, 0), a3, voffA);
;             PG8_WAIT_V(8); PG8_WAIT_L(0); PG8_BAR; PG8_MMA(1, 0, At, B0); PG8_MMA(1, 1, At, B1); PG8_BAR; PG8_SCHED;
;     ...
;         if constexpr (ALIGN_EPI) { if (wr == 0) PG8_BAR; }
	s_add_i32 s67, 0, 0x18000
	s_add_i32 s68, 0, 0x1c000
	ds_read_b128 v[140:143], v246
	ds_read_b128 v[152:155], v246 offset:1024
	ds_read_b128 v[162:165], v246 offset:2048
	ds_read_b128 v[166:169], v246 offset:3072
	ds_read_b128 v[170:173], v247
	ds_read_b128 v[174:177], v247 offset:1024
	ds_read_b128 v[178:181], v247 offset:2048
	ds_read_b128 v[182:185], v247 offset:3072
	s_mov_b32 m0, s47
	s_nop 0
	global_load_lds_dwordx4 v130, s[36:37]
	s_mov_b32 m0, s48
	s_nop 0
	global_load_lds_dwordx4 v132, s[36:37]
	s_add_u32 s36, s36, 0x80000
	s_addc_u32 s37, s37, 0
	s_mov_b32 m0, s49
	ds_read_b128 v[186:189], v150 offset:32768
	ds_read_b128 v[190:193], v150 offset:33792
	ds_read_b128 v[200:203], v150 offset:34816
	ds_read_b128 v[204:207], v150 offset:35840
	ds_read_b128 v[208:211], v150 offset:36864
	ds_read_b128 v[212:215], v150 offset:37888
	ds_read_b128 v[216:219], v150 offset:38912
	ds_read_b128 v[220:223], v150 offset:39936
	global_load_lds_dwordx4 v130, s[36:37]
	s_mov_b32 m0, s50
	s_nop 0
	global_load_lds_dwordx4 v132, s[36:37]
	s_waitcnt vmcnt(8) lgkmcnt(0)
	s_barrier
	v_mfma_f32_16x16x32_bf16 v[126:129], v[140:143], v[186:189], v[126:129]
	v_mfma_f32_16x16x32_bf16 v[122:125], v[162:165], v[186:189], v[122:125]
	v_mfma_f32_16x16x32_bf16 v[110:113], v[140:143], v[200:203], v[110:113]
	v_mfma_f32_16x16x32_bf16 v[106:109], v[162:165], v[200:203], v[106:109]
	v_mfma_f32_16x16x32_bf16 v[94:97], v[140:143], v[208:211], v[94:97]
	v_mfma_f32_16x16x32_bf16 v[90:93], v[162:165], v[208:211], v[90:93]
	v_mfma_f32_16x16x32_bf16 v[78:81], v[140:143], v[216:219], v[78:81]
	v_mfma_f32_16x16x32_bf16 v[74:77], v[162:165], v[216:219], v[74:77]
	v_mfma_f32_16x16x32_bf16 v[126:129], v[152:155], v[190:193], v[126:129]
	v_mfma_f32_16x16x32_bf16 v[122:125], v[166:169], v[190:193], v[122:125]
	v_mfma_f32_16x16x32_bf16 v[110:113], v[152:155], v[204:207], v[110:113]
	v_mfma_f32_16x16x32_bf16 v[106:109], v[166:169], v[204:207], v[106:109]
	v_mfma_f32_16x16x32_bf16 v[94:97], v[152:155], v[212:215], v[94:97]
	v_mfma_f32_16x16x32_bf16 v[90:93], v[166:169], v[212:215], v[90:93]
	v_mfma_f32_16x16x32_bf16 v[78:81], v[152:155], v[220:223], v[78:81]
	v_mfma_f32_16x16x32_bf16 v[74:77], v[166:169], v[220:223], v[74:77]
	v_mfma_f32_16x16x32_bf16 v[118:121], v[170:173], v[186:189], v[118:121]
	v_mfma_f32_16x16x32_bf16 v[114:117], v[178:181], v[186:189], v[114:117]
	v_mfma_f32_16x16x32_bf16 v[102:105], v[170:173], v[200:203], v[102:105]
	v_mfma_f32_16x16x32_bf16 v[98:101], v[178:181], v[200:203], v[98:101]
	v_mfma_f32_16x16x32_bf16 v[86:89], v[170:173], v[208:211], v[86:89]
	v_mfma_f32_16x16x32_bf16 v[82:85], v[178:181], v[208:211], v[82:85]
	v_mfma_f32_16x16x32_bf16 v[70:73], v[170:173], v[216:219], v[70:73]
	v_mfma_f32_16x16x32_bf16 v[66:69], v[178:181], v[216:219], v[66:69]
	v_mfma_f32_16x16x32_bf16 v[118:121], v[174:177], v[190:193], v[118:121]
	v_mfma_f32_16x16x32_bf16 v[114:117], v[182:185], v[190:193], v[114:117]
	v_mfma_f32_16x16x32_bf16 v[102:105], v[174:177], v[204:207], v[102:105]
	v_mfma_f32_16x16x32_bf16 v[98:101], v[182:185], v[204:207], v[98:101]
	v_mfma_f32_16x16x32_bf16 v[86:89], v[174:177], v[212:215], v[86:89]
	v_mfma_f32_16x16x32_bf16 v[82:85], v[182:185], v[212:215], v[82:85]
	v_mfma_f32_16x16x32_bf16 v[70:73], v[174:177], v[220:223], v[70:73]
	v_mfma_f32_16x16x32_bf16 v[66:69], v[182:185], v[220:223], v[66:69]
	s_barrier
	s_add_i32 s36, s67, s46
	s_add_i32 m0, s36, 0xffffff80
	ds_read_b128 v[186:189], v150 offset:49152
	ds_read_b128 v[190:193], v150 offset:50176
	ds_read_b128 v[200:203], v150 offset:51200
	ds_read_b128 v[204:207], v150 offset:52224
	ds_read_b128 v[208:211], v150 offset:53248
	ds_read_b128 v[212:215], v150 offset:54272
	ds_read_b128 v[216:219], v150 offset:55296
	ds_read_b128 v[220:223], v150 offset:56320
	global_load_lds_dwordx4 v158, s[30:31] offset:128
	s_add_i32 m0, s36, 0x1f80
	s_add_i32 s36, s68, s46
	global_load_lds_dwordx4 v134, s[30:31] offset:128
	s_add_u32 s30, s30, 0x80080
	s_addc_u32 s31, s31, 0
	s_mov_b32 m0, s36
	s_nop 0
	global_load_lds_dwordx4 v158, s[30:31]
	s_add_i32 m0, s36, 0x2000
	s_nop 0
	global_load_lds_dwordx4 v134, s[30:31]
	s_waitcnt vmcnt(6) lgkmcnt(0)
	s_barrier
	v_mfma_f32_16x16x32_bf16 v[62:65], v[140:143], v[186:189], v[62:65]
	v_mfma_f32_16x16x32_bf16 v[58:61], v[162:165], v[186:189], v[58:61]
	v_mfma_f32_16x16x32_bf16 v[46:49], v[140:143], v[200:203], v[46:49]
	v_mfma_f32_16x16x32_bf16 v[42:45], v[162:165], v[200:203], v[42:45]
	v_mfma_f32_16x16x32_bf16 v[30:33], v[140:143], v[208:211], v[30:33]
	v_mfma_f32_16x16x32_bf16 v[26:29], v[162:165], v[208:211], v[26:29]
	v_mfma_f32_16x16x32_bf16 v[14:17], v[140:143], v[216:219], v[14:17]
	v_mfma_f32_16x16x32_bf16 v[10:13], v[162:165], v[216:219], v[10:13]
	v_mfma_f32_16x16x32_bf16 v[62:65], v[152:155], v[190:193], v[62:65]
	v_mfma_f32_16x16x32_bf16 v[58:61], v[166:169], v[190:193], v[58:61]
	v_mfma_f32_16x16x32_bf16 v[46:49], v[152:155], v[204:207], v[46:49]
	v_mfma_f32_16x16x32_bf16 v[42:45], v[166:169], v[204:207], v[42:45]
	v_mfma_f32_16x16x32_bf16 v[30:33], v[152:155], v[212:215], v[30:33]
	v_mfma_f32_16x16x32_bf16 v[26:29], v[166:169], v[212:215], v[26:29]
	v_mfma_f32_16x16x32_bf16 v[14:17], v[152:155], v[220:223], v[14:17]
	v_mfma_f32_16x16x32_bf16 v[10:13], v[166:169], v[220:223], v[10:13]
	v_mfma_f32_16x16x32_bf16 v[54:57], v[170:173], v[186:189], v[54:57]
	v_mfma_f32_16x16x32_bf16 v[50:53], v[178:181], v[186:189], v[50:53]
	v_mfma_f32_16x16x32_bf16 v[38:41], v[170:173], v[200:203], v[38:41]
	v_mfma_f32_16x16x32_bf16 v[34:37], v[178:181], v[200:203], v[34:37]
	v_mfma_f32_16x16x32_bf16 v[22:25], v[170:173], v[208:211], v[22:25]
	v_mfma_f32_16x16x32_bf16 v[18:21], v[178:181], v[208:211], v[18:21]
	v_mfma_f32_16x16x32_bf16 v[6:9], v[170:173], v[216:219], v[6:9]
	v_mfma_f32_16x16x32_bf16 v[2:5], v[178:181], v[216:219], v[2:5]
	v_mfma_f32_16x16x32_bf16 v[54:57], v[174:177], v[190:193], v[54:57]
	v_mfma_f32_16x16x32_bf16 v[50:53], v[182:185], v[190:193], v[50:53]
	v_mfma_f32_16x16x32_bf16 v[38:41], v[174:177], v[204:207], v[38:41]
	v_mfma_f32_16x16x32_bf16 v[34:37], v[182:185], v[204:207], v[34:37]
	v_mfma_f32_16x16x32_bf16 v[22:25], v[174:177], v[212:215], v[22:25]
	v_mfma_f32_16x16x32_bf16 v[18:21], v[182:185], v[212:215], v[18:21]
	v_mfma_f32_16x16x32_bf16 v[6:9], v[174:177], v[220:223], v[6:9]
	v_mfma_f32_16x16x32_bf16 v[2:5], v[182:185], v[220:223], v[2:5]
	s_barrier
	s_add_i32 s66, s66, 2
	s_add_u32 s0, s0, 0x100
	s_addc_u32 s1, s1, 0
	s_add_u32 s62, s62, 0x100
	s_addc_u32 s63, s63, 0
	s_cmp_gt_u32 s66, 29
	s_cbranch_scc0 .LBB0_762
	s_and_b64 vcc, exec, s[16:17]
	s_mov_b64 s[60:61], s[90:91]
	s_mov_b64 s[62:63], s[88:89]
	s_cbranch_vccz .LBB0_765
	s_barrier

; #define PG8_STAGE(bufoff, gbase, voff) do { _Pragma("unroll") for (int _i = 0; _i < 2; ++_i) \
;         __builtin_amdgcn_global_load_lds((const unsigned*)((const char*)(gbase) + (voff)[_i]), (PG8_LAS unsigned*)(lds + (bufoff) + ldsw + _i * 8192), 16, 0, 0); } while (0)
; #define PG8_LDA(dst, b, h) do { _Pragma("unroll") for (int m = 0; m < 4; ++m) _Pragma("unroll") for (int k = 0; k < 2; ++k) dst[m][k] = *(const PG8_LAS bf16x8*)(lds + PG8_SA(b, h) + aoff + m * 2048 + k * 1024); } while (0)
; #define PG8_LDB(dst, b, h) do { _Pragma("unroll") for (int n = 0; n < 2; ++n) _Pragma("unroll") for (int k = 0; k < 2; ++k) dst[n][k] = *(const PG8_LAS bf16x8*)(lds + PG8_SB(b, h) + boff + n * 2048 + k * 1024); } while (0)
; #define PG8_MMA(ai, bj, At, Bt) do { __builtin_amdgcn_s_setprio(1); _Pragma("unroll") for (int m = 0; m < 4; ++m) _Pragma("unroll") for (int n = 0; n < 2; ++n) _Pragma("unroll") for (int k = 0; k < 2; ++k) \
;         acc[ai][bj][m][n] = __builtin_amdgcn_mfma_f32_16x16x32_bf16(Bt[n][k], At[m][k], acc[ai][bj][m][n], 0, 0, 0); __builtin_amdgcn_s_setprio(0); } while (0)
; #define PG8_WAIT_V(n) asm volatile("s_waitcnt vmcnt(" #n ")" ::: "memory")
; #define PG8_WAIT_L(n) asm volatile("s_waitcnt lgkmcnt(" #n ")" ::: "memory")
; template <class Epi, class Sched, bool ALIGN_EPI = false, bool SP2 = false>
; __device__ __forceinline__ void gemm_phase(PG8_LAS unsigned char* lds, const Gemm g, const Sched& S, const Epi& E) {
;     ...
;             const bool last = (t == nt - 2);
;             const char* a1 = cA + (size_t)(t + 1) * kstep;
;             const char* a2 = last ? nA : cA + (size_t)(t + 2) * kstep; const char* b2 = last ? nB : cB + (size_t)(t + 2) * kstep;
;             const char* a3 = a2 + kstep; const char* b3 = b2 + kstep;
;             if (last && has_next) S.a_ready(nxt);
;             if constexpr (SP2) {
;             PG8_LDB(B0, 0, 0); PG8_LDB(B1, 0, 1); PG8_SCHED; PG8_LDA(At, 0, 0); PG8_STAGE(PG8_SA(1, 1), a1 + hstep, voffA);
;             PG8_WAIT_V(8); PG8_WAIT_L(0); PG8_BAR; PG8_MMA(0, 0, At, B0); PG8_MMA(0, 1, At, B1); PG8_BAR; PG8_SCHED;
;             PG8_LDA(At, 0, 1); PG8_STAGE(PG8_SB(0, 0), b2, voffB); PG8_STAGE(PG8_SB(0, 1), b2 + hstep, voffB); PG8_STAGE(PG8_SA(0, 0), a2, voffA);
;             PG8_WAIT_V(8); PG8_WAIT_L(0); PG8_BAR; PG8_MMA(1, 0, At, B0); PG8_MMA(1, 1, At, B1); PG8_BAR; PG8_SCHED;
.LBB0_842:
	s_add_u32 s30, s0, 0xffe00080
	s_addc_u32 s31, s1, -1
	s_add_i32 s68, 0, 0x10000
	s_cmpk_eq_i32 s67, 0x7c
	s_cselect_b32 s37, s23, s31
	s_cselect_b32 s36, s61, s30
	s_cselect_b32 s31, s19, s66
	s_cselect_b32 s30, s62, s63
	s_add_i32 s70, 0, 0x14000
	ds_read_b128 v[130:133], v244
	ds_read_b128 v[134:137], v244 offset:1024
	ds_read_b128 v[138:141], v244 offset:2048
	ds_read_b128 v[142:145], v244 offset:3072
	ds_read_b128 v[146:149], v245
	ds_read_b128 v[150:153], v245 offset:1024
	ds_read_b128 v[154:157], v245 offset:2048
	ds_read_b128 v[162:165], v245 offset:3072
	s_add_u32 s98, s0, 0xffe00000
	s_addc_u32 s99, s1, -1
	s_mov_b32 m0, s56
	s_nop 0
	global_load_lds_dwordx4 v172, s[98:99]
	s_mov_b32 m0, s57
	s_nop 0
	global_load_lds_dwordx4 v174, s[98:99]
	s_add_i32 m0, s51, 0xc000
	ds_read_b128 v[176:179], v201
	ds_read_b128 v[180:183], v201 offset:1024
	ds_read_b128 v[184:187], v201 offset:2048
	ds_read_b128 v[188:191], v201 offset:3072
	ds_read_b128 v[202:205], v201 offset:4096
	ds_read_b128 v[206:209], v201 offset:5120
	ds_read_b128 v[210:213], v201 offset:6144
	ds_read_b128 v[214:217], v201 offset:7168
	global_load_lds_dwordx4 v172, s[0:1]
	s_add_i32 m0, s51, 0xe000
	s_nop 0
	global_load_lds_dwordx4 v174, s[0:1]
	s_waitcnt vmcnt(8) lgkmcnt(0)
	s_barrier
	v_mfma_f32_16x16x32_bf16 v[126:129], v[130:133], v[176:179], v[126:129]
	v_mfma_f32_16x16x32_bf16 v[122:125], v[138:141], v[176:179], v[122:125]
	v_mfma_f32_16x16x32_bf16 v[110:113], v[130:133], v[184:187], v[110:113]
	v_mfma_f32_16x16x32_bf16 v[106:109], v[138:141], v[184:187], v[106:109]
	v_mfma_f32_16x16x32_bf16 v[94:97], v[130:133], v[202:205], v[94:97]
	v_mfma_f32_16x16x32_bf16 v[90:93], v[138:141], v[202:205], v[90:93]
	v_mfma_f32_16x16x32_bf16 v[78:81], v[130:133], v[210:213], v[78:81]
	v_mfma_f32_16x16x32_bf16 v[74:77], v[138:141], v[210:213], v[74:77]
	v_mfma_f32_16x16x32_bf16 v[126:129], v[134:137], v[180:183], v[126:129]
	v_mfma_f32_16x16x32_bf16 v[122:125], v[142:145], v[180:183], v[122:125]
	v_mfma_f32_16x16x32_bf16 v[110:113], v[134:137], v[188:191], v[110:113]
	v_mfma_f32_16x16x32_bf16 v[106:109], v[142:145], v[188:191], v[106:109]
	v_mfma_f32_16x16x32_bf16 v[94:97], v[134:137], v[206:209], v[94:97]
	v_mfma_f32_16x16x32_bf16 v[90:93], v[142:145], v[206:209], v[90:93]
	v_mfma_f32_16x16x32_bf16 v[78:81], v[134:137], v[214:217], v[78:81]
	v_mfma_f32_16x16x32_bf16 v[74:77], v[142:145], v[214:217], v[74:77]
	v_mfma_f32_16x16x32_bf16 v[118:121], v[146:149], v[176:179], v[118:121]
	v_mfma_f32_16x16x32_bf16 v[114:117], v[154:157], v[176:179], v[114:117]
	v_mfma_f32_16x16x32_bf16 v[102:105], v[146:149], v[184:187], v[102:105]
	v_mfma_f32_16x16x32_bf16 v[98:101], v[154:157], v[184:187], v[98:101]
	v_mfma_f32_16x16x32_bf16 v[86:89], v[146:149], v[202:205], v[86:89]
	v_mfma_f32_16x16x32_bf16 v[82:85], v[154:157], v[202:205], v[82:85]
	v_mfma_f32_16x16x32_bf16 v[70:73], v[146:149], v[210:213], v[70:73]
	v_mfma_f32_16x16x32_bf16 v[66:69], v[154:157], v[210:213], v[66:69]
	v_mfma_f32_16x16x32_bf16 v[118:121], v[150:153], v[180:183], v[118:121]
	v_mfma_f32_16x16x32_bf16 v[114:117], v[162:165], v[180:183], v[114:117]
	v_mfma_f32_16x16x32_bf16 v[102:105], v[150:153], v[188:191], v[102:105]
	v_mfma_f32_16x16x32_bf16 v[98:101], v[162:165], v[188:191], v[98:101]
	v_mfma_f32_16x16x32_bf16 v[86:89], v[150:153], v[206:209], v[86:89]
	v_mfma_f32_16x16x32_bf16 v[82:85], v[162:165], v[206:209], v[82:85]
	v_mfma_f32_16x16x32_bf16 v[70:73], v[150:153], v[214:217], v[70:73]
	v_mfma_f32_16x16x32_bf16 v[66:69], v[162:165], v[214:217], v[66:69]
	s_barrier
	s_add_i32 s68, s68, s50
	s_mov_b32 m0, s68
	ds_read_b128 v[176:179], v201 offset:16384
	ds_read_b128 v[180:183], v201 offset:17408
	ds_read_b128 v[184:187], v201 offset:18432
	ds_read_b128 v[188:191], v201 offset:19456
	ds_read_b128 v[202:205], v201 offset:20480
	ds_read_b128 v[206:209], v201 offset:21504
	ds_read_b128 v[210:213], v201 offset:22528
	ds_read_b128 v[214:217], v201 offset:23552
	global_load_lds_dwordx4 v158, s[30:31]
	s_add_i32 m0, s68, 0x2000
	s_add_u32 s68, s30, 0x200000
	s_addc_u32 s69, s31, 0
	s_add_i32 s70, s70, s50
	global_load_lds_dwordx4 v166, s[30:31]
	s_mov_b32 m0, s70
	s_nop 0
	global_load_lds_dwordx4 v158, s[68:69]
	s_add_i32 m0, s70, 0x2000
	s_nop 0
	global_load_lds_dwordx4 v166, s[68:69]
	s_waitcnt vmcnt(6) lgkmcnt(0)
	s_barrier
	v_mfma_f32_16x16x32_bf16 v[62:65], v[130:133], v[176:179], v[62:65]
	v_mfma_f32_16x16x32_bf16 v[58:61], v[138:141], v[176:179], v[58:61]
	v_mfma_f32_16x16x32_bf16 v[46:49], v[130:133], v[184:187], v[46:49]
	v_mfma_f32_16x16x32_bf16 v[42:45], v[138:141], v[184:187], v[42:45]
	v_mfma_f32_16x16x32_bf16 v[30:33], v[130:133], v[202:205], v[30:33]
	v_mfma_f32_16x16x32_bf16 v[26:29], v[138:141], v[202:205], v[26:29]
	v_mfma_f32_16x16x32_bf16 v[14:17], v[130:133], v[210:213], v[14:17]
	v_mfma_f32_16x16x32_bf16 v[10:13], v[138:141], v[210:213], v[10:13]
	v_mfma_f32_16x16x32_bf16 v[62:65], v[134:137], v[180:183], v[62:65]
	v_mfma_f32_16x16x32_bf16 v[58:61], v[142:145], v[180:183], v[58:61]
	v_mfma_f32_16x16x32_bf16 v[46:49], v[134:137], v[188:191], v[46:49]
	v_mfma_f32_16x16x32_bf16 v[42:45], v[142:145], v[188:191], v[42:45]
	v_mfma_f32_16x16x32_bf16 v[30:33], v[134:137], v[206:209], v[30:33]
	v_mfma_f32_16x16x32_bf16 v[26:29], v[142:145], v[206:209], v[26:29]
	v_mfma_f32_16x16x32_bf16 v[14:17], v[134:137], v[214:217], v[14:17]
	v_mfma_f32_16x16x32_bf16 v[10:13], v[142:145], v[214:217], v[10:13]
	v_mfma_f32_16x16x32_bf16 v[54:57], v[146:149], v[176:179], v[54:57]
	v_mfma_f32_16x16x32_bf16 v[50:53], v[154:157], v[176:179], v[50:53]
	v_mfma_f32_16x16x32_bf16 v[38:41], v[146:149], v[184:187], v[38:41]
	v_mfma_f32_16x16x32_bf16 v[34:37], v[154:157], v[184:187], v[34:37]
	v_mfma_f32_16x16x32_bf16 v[22:25], v[146:149], v[202:205], v[22:25]
	v_mfma_f32_16x16x32_bf16 v[18:21], v[154:157], v[202:205], v[18:21]
	v_mfma_f32_16x16x32_bf16 v[6:9], v[146:149], v[210:213], v[6:9]
	v_mfma_f32_16x16x32_bf16 v[2:5], v[154:157], v[210:213], v[2:5]
	v_mfma_f32_16x16x32_bf16 v[54:57], v[150:153], v[180:183], v[54:57]
	v_mfma_f32_16x16x32_bf16 v[50:53], v[162:165], v[180:183], v[50:53]
	v_mfma_f32_16x16x32_bf16 v[38:41], v[150:153], v[188:191], v[38:41]
	v_mfma_f32_16x16x32_bf16 v[34:37], v[162:165], v[188:191], v[34:37]
	v_mfma_f32_16x16x32_bf16 v[22:25], v[150:153], v[206:209], v[22:25]
	v_mfma_f32_16x16x32_bf16 v[18:21], v[162:165], v[206:209], v[18:21]
	v_mfma_f32_16x16x32_bf16 v[6:9], v[150:153], v[214:217], v[6:9]
	v_mfma_f32_16x16x32_bf16 v[2:5], v[162:165], v[214:217], v[2:5]
	s_barrier
; #define PG8_STAGE(bufoff, gbase, voff) do { _Pragma("unroll") for (int _i = 0; _i < 2; ++_i) \
;         __builtin_amdgcn_global_load_lds((const unsigned*)((const char*)(gbase) + (voff)[_i]), (PG8_LAS unsigned*)(lds + (bufoff) + ldsw + _i * 8192), 16, 0, 0); } while (0)
; #define PG8_LDA(dst, b, h) do { _Pragma("unroll") for (int m = 0; m < 4; ++m) _Pragma("unroll") for (int k = 0; k < 2; ++k) dst[m][k] = *(const PG8_LAS bf16x8*)(lds + PG8_SA(b, h) + aoff + m * 2048 + k * 1024); } while (0)
; #define PG8_WAIT_V(n) asm volatile("s_waitcnt vmcnt(" #n ")" ::: "memory")
; #define PG8_WAIT_L(n) asm volatile("s_waitcnt lgkmcnt(" #n ")" ::: "memory")
; template <class Epi, class Sched, bool ALIGN_EPI = false, bool SP2 = false>
; __device__ __forceinline__ void gemm_phase(PG8_LAS unsigned char* lds, const Gemm g, const Sched& S, const Epi& E) {
;     ...
;         for (int t = 0; t < nt; t += 2) {
;             const bool last = (t == nt - 2);
;             const char* a1 = cA + (size_t)(t + 1) * kstep;
;             const char* a2 = last ? nA : cA + (size_t)(t + 2) * kstep; const char* b2 = last ? nB : cB + (size_t)(t + 2) * kstep;
;             const char* a3 = a2 + kstep; const char* b3 = b2 + kstep;
;             if (last && has_next) S.a_ready(nxt);
;             if constexpr (SP2) {
;             PG8_LDB(B0, 0, 0); PG8_LDB(B1, 0, 1); PG8_SCHED; PG8_LDA(At, 0, 0); PG8_STAGE(PG8_SA(1, 1), a1 + hstep, voffA);
;             PG8_WAIT_V(8); PG8_WAIT_L(0); PG8_BAR; PG8_MMA(0, 0, At, B0); PG8_MMA(0, 1, At, B1); PG8_BAR; PG8_SCHED;
;             PG8_LDA(At, 0, 1); PG8_STAGE(PG8_SB(0, 0), b2, voffB); PG8_STAGE(PG8_SB(0, 1), b2 + hstep, voffB); PG8_STAGE(PG8_SA(0, 0), a2, voffA);
;             PG8_WAIT_V(8); PG8_WAIT_L(0); PG8_BAR; PG8_MMA(1, 0, At, B0); PG8_MMA(1, 1, At, B1); PG8_BAR; PG8_SCHED;
;             PG8_LDB(B0, 1, 0); PG8_LDB(B1, 1, 1); PG8_SCHED; PG8_LDA(At, 1, 0); PG8_STAGE(PG8_SA(0, 1), a2 + hstep, voffA);
;             PG8_WAIT_V(8); PG8_WAIT_L(0); PG8_BAR; PG8_MMA(0, 0, At, B0); PG8_MMA(0, 1, At, B1); PG8_BAR; PG8_SCHED;
;             PG8_LDA(At, 1, 1); PG8_STAGE(PG8_SB(1, 0), b3, voffB); PG8_STAGE(PG8_SB(1, 1), b3 + hstep, voffB); PG8_STAGE(PG8_SA(1, 0), a3, voffA);
;             PG8_WAIT_V(8); PG8_WAIT_L(0); PG8_BAR; PG8_MMA(1, 0, At, B0); PG8_MMA(1, 1, At, B1); PG8_BAR; PG8_SCHED;
;     ...
;         if constexpr (ALIGN_EPI) { if (wr == 0) PG8_BAR; }
	s_add_i32 s68, 0, 0x18000
	s_add_i32 s69, 0, 0x1c000
	ds_read_b128 v[130:133], v246
	ds_read_b128 v[134:137], v246 offset:1024
	ds_read_b128 v[138:141], v246 offset:2048
	ds_read_b128 v[142:145], v246 offset:3072
	ds_read_b128 v[146:149], v247
	ds_read_b128 v[150:153], v247 offset:1024
	ds_read_b128 v[154:157], v247 offset:2048
	ds_read_b128 v[162:165], v247 offset:3072
	s_mov_b32 m0, s51
	s_nop 0
	global_load_lds_dwordx4 v170, s[36:37]
	s_mov_b32 m0, s52
	s_nop 0
	global_load_lds_dwordx4 v168, s[36:37]
	s_add_u32 s36, s36, 0x200000
	s_addc_u32 s37, s37, 0
	s_mov_b32 m0, s53
	ds_read_b128 v[176:179], v201 offset:32768
	ds_read_b128 v[180:183], v201 offset:33792
	ds_read_b128 v[184:187], v201 offset:34816
	ds_read_b128 v[188:191], v201 offset:35840
	ds_read_b128 v[202:205], v201 offset:36864
	ds_read_b128 v[206:209], v201 offset:37888
	ds_read_b128 v[210:213], v201 offset:38912
	ds_read_b128 v[214:217], v201 offset:39936
	global_load_lds_dwordx4 v170, s[36:37]
	s_mov_b32 m0, s54
	s_nop 0
	global_load_lds_dwordx4 v168, s[36:37]
	s_waitcnt vmcnt(8) lgkmcnt(0)
	s_barrier
	v_mfma_f32_16x16x32_bf16 v[126:129], v[130:133], v[176:179], v[126:129]
	v_mfma_f32_16x16x32_bf16 v[122:125], v[138:141], v[176:179], v[122:125]
	v_mfma_f32_16x16x32_bf16 v[110:113], v[130:133], v[184:187], v[110:113]
	v_mfma_f32_16x16x32_bf16 v[106:109], v[138:141], v[184:187], v[106:109]
	v_mfma_f32_16x16x32_bf16 v[94:97], v[130:133], v[202:205], v[94:97]
	v_mfma_f32_16x16x32_bf16 v[90:93], v[138:141], v[202:205], v[90:93]
	v_mfma_f32_16x16x32_bf16 v[78:81], v[130:133], v[210:213], v[78:81]
	v_mfma_f32_16x16x32_bf16 v[74:77], v[138:141], v[210:213], v[74:77]
	v_mfma_f32_16x16x32_bf16 v[126:129], v[134:137], v[180:183], v[126:129]
	v_mfma_f32_16x16x32_bf16 v[122:125], v[142:145], v[180:183], v[122:125]
	v_mfma_f32_16x16x32_bf16 v[110:113], v[134:137], v[188:191], v[110:113]
	v_mfma_f32_16x16x32_bf16 v[106:109], v[142:145], v[188:191], v[106:109]
	v_mfma_f32_16x16x32_bf16 v[94:97], v[134:137], v[206:209], v[94:97]
	v_mfma_f32_16x16x32_bf16 v[90:93], v[142:145], v[206:209], v[90:93]
	v_mfma_f32_16x16x32_bf16 v[78:81], v[134:137], v[214:217], v[78:81]
	v_mfma_f32_16x16x32_bf16 v[74:77], v[142:145], v[214:217], v[74:77]
	v_mfma_f32_16x16x32_bf16 v[118:121], v[146:149], v[176:179], v[118:121]
	v_mfma_f32_16x16x32_bf16 v[114:117], v[154:157], v[176:179], v[114:117]
	v_mfma_f32_16x16x32_bf16 v[102:105], v[146:149], v[184:187], v[102:105]
	v_mfma_f32_16x16x32_bf16 v[98:101], v[154:157], v[184:187], v[98:101]
	v_mfma_f32_16x16x32_bf16 v[86:89], v[146:149], v[202:205], v[86:89]
	v_mfma_f32_16x16x32_bf16 v[82:85], v[154:157], v[202:205], v[82:85]
	v_mfma_f32_16x16x32_bf16 v[70:73], v[146:149], v[210:213], v[70:73]
	v_mfma_f32_16x16x32_bf16 v[66:69], v[154:157], v[210:213], v[66:69]
	v_mfma_f32_16x16x32_bf16 v[118:121], v[150:153], v[180:183], v[118:121]
	v_mfma_f32_16x16x32_bf16 v[114:117], v[162:165], v[180:183], v[114:117]
	v_mfma_f32_16x16x32_bf16 v[102:105], v[150:153], v[188:191], v[102:105]
	v_mfma_f32_16x16x32_bf16 v[98:101], v[162:165], v[188:191], v[98:101]
	v_mfma_f32_16x16x32_bf16 v[86:89], v[150:153], v[206:209], v[86:89]
	v_mfma_f32_16x16x32_bf16 v[82:85], v[162:165], v[206:209], v[82:85]
	v_mfma_f32_16x16x32_bf16 v[70:73], v[150:153], v[214:217], v[70:73]
	v_mfma_f32_16x16x32_bf16 v[66:69], v[162:165], v[214:217], v[66:69]
	s_barrier
	s_add_i32 s36, s68, s50
	s_add_i32 m0, s36, 0xffffff80
	ds_read_b128 v[176:179], v201 offset:49152
	ds_read_b128 v[180:183], v201 offset:50176
	ds_read_b128 v[184:187], v201 offset:51200
	ds_read_b128 v[188:191], v201 offset:52224
	ds_read_b128 v[202:205], v201 offset:53248
	ds_read_b128 v[206:209], v201 offset:54272
	ds_read_b128 v[210:213], v201 offset:55296
	ds_read_b128 v[214:217], v201 offset:56320
	global_load_lds_dwordx4 v158, s[30:31] offset:128
	s_add_i32 m0, s36, 0x1f80
	s_add_i32 s36, s69, s50
	global_load_lds_dwordx4 v166, s[30:31] offset:128
	s_add_u32 s30, s30, 0x200080
	s_addc_u32 s31, s31, 0
	s_mov_b32 m0, s36
	s_nop 0
	global_load_lds_dwordx4 v158, s[30:31]
	s_add_i32 m0, s36, 0x2000
	s_nop 0
	global_load_lds_dwordx4 v166, s[30:31]
	s_waitcnt vmcnt(6) lgkmcnt(0)
	s_barrier
	v_mfma_f32_16x16x32_bf16 v[62:65], v[130:133], v[176:179], v[62:65]
	v_mfma_f32_16x16x32_bf16 v[58:61], v[138:141], v[176:179], v[58:61]
	v_mfma_f32_16x16x32_bf16 v[46:49], v[130:133], v[184:187], v[46:49]
	v_mfma_f32_16x16x32_bf16 v[42:45], v[138:141], v[184:187], v[42:45]
	v_mfma_f32_16x16x32_bf16 v[30:33], v[130:133], v[202:205], v[30:33]
	v_mfma_f32_16x16x32_bf16 v[26:29], v[138:141], v[202:205], v[26:29]
	v_mfma_f32_16x16x32_bf16 v[14:17], v[130:133], v[210:213], v[14:17]
	v_mfma_f32_16x16x32_bf16 v[10:13], v[138:141], v[210:213], v[10:13]
	v_mfma_f32_16x16x32_bf16 v[62:65], v[134:137], v[180:183], v[62:65]
	v_mfma_f32_16x16x32_bf16 v[58:61], v[142:145], v[180:183], v[58:61]
	v_mfma_f32_16x16x32_bf16 v[46:49], v[134:137], v[188:191], v[46:49]
	v_mfma_f32_16x16x32_bf16 v[42:45], v[142:145], v[188:191], v[42:45]
	v_mfma_f32_16x16x32_bf16 v[30:33], v[134:137], v[206:209], v[30:33]
	v_mfma_f32_16x16x32_bf16 v[26:29], v[142:145], v[206:209], v[26:29]
	v_mfma_f32_16x16x32_bf16 v[14:17], v[134:137], v[214:217], v[14:17]
	v_mfma_f32_16x16x32_bf16 v[10:13], v[142:145], v[214:217], v[10:13]
	v_mfma_f32_16x16x32_bf16 v[54:57], v[146:149], v[176:179], v[54:57]
	v_mfma_f32_16x16x32_bf16 v[50:53], v[154:157], v[176:179], v[50:53]
	v_mfma_f32_16x16x32_bf16 v[38:41], v[146:149], v[184:187], v[38:41]
	v_mfma_f32_16x16x32_bf16 v[34:37], v[154:157], v[184:187], v[34:37]
	v_mfma_f32_16x16x32_bf16 v[22:25], v[146:149], v[202:205], v[22:25]
	v_mfma_f32_16x16x32_bf16 v[18:21], v[154:157], v[202:205], v[18:21]
	v_mfma_f32_16x16x32_bf16 v[6:9], v[146:149], v[210:213], v[6:9]
	v_mfma_f32_16x16x32_bf16 v[2:5], v[154:157], v[210:213], v[2:5]
	v_mfma_f32_16x16x32_bf16 v[54:57], v[150:153], v[180:183], v[54:57]
	v_mfma_f32_16x16x32_bf16 v[50:53], v[162:165], v[180:183], v[50:53]
	v_mfma_f32_16x16x32_bf16 v[38:41], v[150:153], v[188:191], v[38:41]
	v_mfma_f32_16x16x32_bf16 v[34:37], v[162:165], v[188:191], v[34:37]
	v_mfma_f32_16x16x32_bf16 v[22:25], v[150:153], v[206:209], v[22:25]
	v_mfma_f32_16x16x32_bf16 v[18:21], v[162:165], v[206:209], v[18:21]
	v_mfma_f32_16x16x32_bf16 v[6:9], v[150:153], v[214:217], v[6:9]
	v_mfma_f32_16x16x32_bf16 v[2:5], v[162:165], v[214:217], v[2:5]
	s_barrier
	s_add_i32 s67, s67, 2
	s_add_u32 s0, s0, 0x100
	s_addc_u32 s1, s1, 0
	s_add_u32 s63, s63, 0x100
	s_addc_u32 s66, s66, 0
	s_cmpk_gt_u32 s67, 0x7d
	s_cbranch_scc0 .LBB0_842
	s_and_b64 vcc, exec, s[16:17]
	s_cbranch_vccz .LBB0_845
	s_barrier

; #define PG8_STAGE(bufoff, gbase, voff) do { _Pragma("unroll") for (int _i = 0; _i < 2; ++_i) \
;         __builtin_amdgcn_global_load_lds((const unsigned*)((const char*)(gbase) + (voff)[_i]), (PG8_LAS unsigned*)(lds + (bufoff) + ldsw + _i * 8192), 16, 0, 0); } while (0)
; #define PG8_LDA(dst, b, h) do { _Pragma("unroll") for (int m = 0; m < 4; ++m) _Pragma("unroll") for (int k = 0; k < 2; ++k) dst[m][k] = *(const PG8_LAS bf16x8*)(lds + PG8_SA(b, h) + aoff + m * 2048 + k * 1024); } while (0)
; #define PG8_LDB(dst, b, h) do { _Pragma("unroll") for (int n = 0; n < 2; ++n) _Pragma("unroll") for (int k = 0; k < 2; ++k) dst[n][k] = *(const PG8_LAS bf16x8*)(lds + PG8_SB(b, h) + boff + n * 2048 + k * 1024); } while (0)
; #define PG8_MMA(ai, bj, At, Bt) do { __builtin_amdgcn_s_setprio(1); _Pragma("unroll") for (int m = 0; m < 4; ++m) _Pragma("unroll") for (int n = 0; n < 2; ++n) _Pragma("unroll") for (int k = 0; k < 2; ++k) \
;         acc[ai][bj][m][n] = __builtin_amdgcn_mfma_f32_16x16x32_bf16(Bt[n][k], At[m][k], acc[ai][bj][m][n], 0, 0, 0); __builtin_amdgcn_s_setprio(0); } while (0)
; #define PG8_WAIT_V(n) asm volatile("s_waitcnt vmcnt(" #n ")" ::: "memory")
; #define PG8_WAIT_L(n) asm volatile("s_waitcnt lgkmcnt(" #n ")" ::: "memory")
; template <class Epi, class Sched, bool ALIGN_EPI = false, bool SP2 = false>
; __device__ __forceinline__ void gemm_phase(PG8_LAS unsigned char* lds, const Gemm g, const Sched& S, const Epi& E) {
;     ...
;             const bool last = (t == nt - 2);
;             const char* a1 = cA + (size_t)(t + 1) * kstep;
;             const char* a2 = last ? nA : cA + (size_t)(t + 2) * kstep; const char* b2 = last ? nB : cB + (size_t)(t + 2) * kstep;
;             const char* a3 = a2 + kstep; const char* b3 = b2 + kstep;
;             if (last && has_next) S.a_ready(nxt);
;             if constexpr (SP2) {
;             PG8_LDB(B0, 0, 0); PG8_LDB(B1, 0, 1); PG8_SCHED; PG8_LDA(At, 0, 0); PG8_STAGE(PG8_SA(1, 1), a1 + hstep, voffA);
;             PG8_WAIT_V(8); PG8_WAIT_L(0); PG8_BAR; PG8_MMA(0, 0, At, B0); PG8_MMA(0, 1, At, B1); PG8_BAR; PG8_SCHED;
;             PG8_LDA(At, 0, 1); PG8_STAGE(PG8_SB(0, 0), b2, voffB); PG8_STAGE(PG8_SB(0, 1), b2 + hstep, voffB); PG8_STAGE(PG8_SA(0, 0), a2, voffA);
;             PG8_WAIT_V(8); PG8_WAIT_L(0); PG8_BAR; PG8_MMA(1, 0, At, B0); PG8_MMA(1, 1, At, B1); PG8_BAR; PG8_SCHED;
.LBB0_880:
	s_add_u32 s28, s0, 0xffe00080
	s_addc_u32 s29, s1, -1
	s_add_i32 s59, 0, 0x10000
	s_cmpk_eq_i32 s58, 0x7c
	s_cselect_b32 s31, s19, s29
	s_cselect_b32 s30, s54, s28
	s_cselect_b32 s29, s17, s57
	s_cselect_b32 s28, s55, s56
	s_add_i32 s62, 0, 0x14000
	ds_read_b128 v[130:133], v244
	ds_read_b128 v[134:137], v244 offset:1024
	ds_read_b128 v[138:141], v244 offset:2048
	ds_read_b128 v[142:145], v244 offset:3072
	ds_read_b128 v[146:149], v245
	ds_read_b128 v[162:165], v245 offset:1024
	ds_read_b128 v[168:171], v245 offset:2048
	ds_read_b128 v[172:175], v245 offset:3072
	s_add_u32 s98, s0, 0xffe00000
	s_addc_u32 s99, s1, -1
	s_mov_b32 m0, s44
	s_nop 0
	global_load_lds_dwordx4 v156, s[98:99]
	s_mov_b32 m0, s45
	s_nop 0
	global_load_lds_dwordx4 v166, s[98:99]
	s_add_i32 m0, s36, 0xc000
	ds_read_b128 v[182:185], v180
	ds_read_b128 v[186:189], v180 offset:1024
	ds_read_b128 v[190:193], v180 offset:2048
	ds_read_b128 v[200:203], v180 offset:3072
	ds_read_b128 v[204:207], v180 offset:4096
	ds_read_b128 v[208:211], v180 offset:5120
	ds_read_b128 v[212:215], v180 offset:6144
	ds_read_b128 v[216:219], v180 offset:7168
	global_load_lds_dwordx4 v156, s[0:1]
	s_add_i32 m0, s36, 0xe000
	s_nop 0
	global_load_lds_dwordx4 v166, s[0:1]
	s_waitcnt vmcnt(8) lgkmcnt(0)
	s_barrier
	v_mfma_f32_16x16x32_bf16 v[126:129], v[130:133], v[182:185], v[126:129]
	v_mfma_f32_16x16x32_bf16 v[122:125], v[138:141], v[182:185], v[122:125]
	v_mfma_f32_16x16x32_bf16 v[118:121], v[130:133], v[190:193], v[118:121]
	v_mfma_f32_16x16x32_bf16 v[114:117], v[138:141], v[190:193], v[114:117]
	v_mfma_f32_16x16x32_bf16 v[94:97], v[130:133], v[204:207], v[94:97]
	v_mfma_f32_16x16x32_bf16 v[90:93], v[138:141], v[204:207], v[90:93]
	v_mfma_f32_16x16x32_bf16 v[82:85], v[130:133], v[212:215], v[82:85]
	v_mfma_f32_16x16x32_bf16 v[74:77], v[138:141], v[212:215], v[74:77]
	v_mfma_f32_16x16x32_bf16 v[126:129], v[134:137], v[186:189], v[126:129]
	v_mfma_f32_16x16x32_bf16 v[122:125], v[142:145], v[186:189], v[122:125]
	v_mfma_f32_16x16x32_bf16 v[118:121], v[134:137], v[200:203], v[118:121]
	v_mfma_f32_16x16x32_bf16 v[114:117], v[142:145], v[200:203], v[114:117]
	v_mfma_f32_16x16x32_bf16 v[94:97], v[134:137], v[208:211], v[94:97]
	v_mfma_f32_16x16x32_bf16 v[90:93], v[142:145], v[208:211], v[90:93]
	v_mfma_f32_16x16x32_bf16 v[82:85], v[134:137], v[216:219], v[82:85]
	v_mfma_f32_16x16x32_bf16 v[74:77], v[142:145], v[216:219], v[74:77]
	v_mfma_f32_16x16x32_bf16 v[110:113], v[146:149], v[182:185], v[110:113]
	v_mfma_f32_16x16x32_bf16 v[106:109], v[168:171], v[182:185], v[106:109]
	v_mfma_f32_16x16x32_bf16 v[102:105], v[146:149], v[190:193], v[102:105]
	v_mfma_f32_16x16x32_bf16 v[98:101], v[168:171], v[190:193], v[98:101]
	v_mfma_f32_16x16x32_bf16 v[86:89], v[146:149], v[204:207], v[86:89]
	v_mfma_f32_16x16x32_bf16 v[78:81], v[168:171], v[204:207], v[78:81]
	v_mfma_f32_16x16x32_bf16 v[70:73], v[146:149], v[212:215], v[70:73]
	v_mfma_f32_16x16x32_bf16 v[66:69], v[168:171], v[212:215], v[66:69]
	v_mfma_f32_16x16x32_bf16 v[110:113], v[162:165], v[186:189], v[110:113]
	v_mfma_f32_16x16x32_bf16 v[106:109], v[172:175], v[186:189], v[106:109]
	v_mfma_f32_16x16x32_bf16 v[102:105], v[162:165], v[200:203], v[102:105]
	v_mfma_f32_16x16x32_bf16 v[98:101], v[172:175], v[200:203], v[98:101]
	v_mfma_f32_16x16x32_bf16 v[86:89], v[162:165], v[208:211], v[86:89]
	v_mfma_f32_16x16x32_bf16 v[78:81], v[172:175], v[208:211], v[78:81]
	v_mfma_f32_16x16x32_bf16 v[70:73], v[162:165], v[216:219], v[70:73]
	v_mfma_f32_16x16x32_bf16 v[66:69], v[172:175], v[216:219], v[66:69]
	s_barrier
	s_add_i32 s59, s59, s34
	s_mov_b32 m0, s59
	ds_read_b128 v[182:185], v180 offset:16384
	ds_read_b128 v[186:189], v180 offset:17408
	ds_read_b128 v[190:193], v180 offset:18432
	ds_read_b128 v[200:203], v180 offset:19456
	ds_read_b128 v[204:207], v180 offset:20480
	ds_read_b128 v[208:211], v180 offset:21504
	ds_read_b128 v[212:215], v180 offset:22528
	ds_read_b128 v[216:219], v180 offset:23552
	global_load_lds_dwordx4 v158, s[28:29]
	s_add_i32 m0, s59, 0x2000
	s_add_u32 s60, s28, 0x200000
	s_addc_u32 s61, s29, 0
	s_add_i32 s59, s62, s34
	global_load_lds_dwordx4 v150, s[28:29]
	s_mov_b32 m0, s59
	s_nop 0
	global_load_lds_dwordx4 v158, s[60:61]
	s_add_i32 m0, s59, 0x2000
	s_nop 0
	global_load_lds_dwordx4 v150, s[60:61]
	s_waitcnt vmcnt(6) lgkmcnt(0)
	s_barrier
	v_mfma_f32_16x16x32_bf16 v[62:65], v[130:133], v[182:185], v[62:65]
	v_mfma_f32_16x16x32_bf16 v[58:61], v[138:141], v[182:185], v[58:61]
	v_mfma_f32_16x16x32_bf16 v[50:53], v[130:133], v[190:193], v[50:53]
	v_mfma_f32_16x16x32_bf16 v[42:45], v[138:141], v[190:193], v[42:45]
	v_mfma_f32_16x16x32_bf16 v[34:37], v[130:133], v[204:207], v[34:37]
	v_mfma_f32_16x16x32_bf16 v[26:29], v[138:141], v[204:207], v[26:29]
	v_mfma_f32_16x16x32_bf16 v[18:21], v[130:133], v[212:215], v[18:21]
	v_mfma_f32_16x16x32_bf16 v[10:13], v[138:141], v[212:215], v[10:13]
	v_mfma_f32_16x16x32_bf16 v[62:65], v[134:137], v[186:189], v[62:65]
	v_mfma_f32_16x16x32_bf16 v[58:61], v[142:145], v[186:189], v[58:61]
	v_mfma_f32_16x16x32_bf16 v[50:53], v[134:137], v[200:203], v[50:53]
	v_mfma_f32_16x16x32_bf16 v[42:45], v[142:145], v[200:203], v[42:45]
	v_mfma_f32_16x16x32_bf16 v[34:37], v[134:137], v[208:211], v[34:37]
	v_mfma_f32_16x16x32_bf16 v[26:29], v[142:145], v[208:211], v[26:29]
	v_mfma_f32_16x16x32_bf16 v[18:21], v[134:137], v[216:219], v[18:21]
	v_mfma_f32_16x16x32_bf16 v[10:13], v[142:145], v[216:219], v[10:13]
	v_mfma_f32_16x16x32_bf16 v[54:57], v[146:149], v[182:185], v[54:57]
	v_mfma_f32_16x16x32_bf16 v[46:49], v[168:171], v[182:185], v[46:49]
	v_mfma_f32_16x16x32_bf16 v[38:41], v[146:149], v[190:193], v[38:41]
	v_mfma_f32_16x16x32_bf16 v[30:33], v[168:171], v[190:193], v[30:33]
	v_mfma_f32_16x16x32_bf16 v[22:25], v[146:149], v[204:207], v[22:25]
	v_mfma_f32_16x16x32_bf16 v[14:17], v[168:171], v[204:207], v[14:17]
	v_mfma_f32_16x16x32_bf16 v[6:9], v[146:149], v[212:215], v[6:9]
	v_mfma_f32_16x16x32_bf16 v[2:5], v[168:171], v[212:215], v[2:5]
	v_mfma_f32_16x16x32_bf16 v[54:57], v[162:165], v[186:189], v[54:57]
	v_mfma_f32_16x16x32_bf16 v[46:49], v[172:175], v[186:189], v[46:49]
	v_mfma_f32_16x16x32_bf16 v[38:41], v[162:165], v[200:203], v[38:41]
	v_mfma_f32_16x16x32_bf16 v[30:33], v[172:175], v[200:203], v[30:33]
	v_mfma_f32_16x16x32_bf16 v[22:25], v[162:165], v[208:211], v[22:25]
	v_mfma_f32_16x16x32_bf16 v[14:17], v[172:175], v[208:211], v[14:17]
	v_mfma_f32_16x16x32_bf16 v[6:9], v[162:165], v[216:219], v[6:9]
	v_mfma_f32_16x16x32_bf16 v[2:5], v[172:175], v[216:219], v[2:5]
	s_barrier
; #define PG8_STAGE(bufoff, gbase, voff) do { _Pragma("unroll") for (int _i = 0; _i < 2; ++_i) \
;         __builtin_amdgcn_global_load_lds((const unsigned*)((const char*)(gbase) + (voff)[_i]), (PG8_LAS unsigned*)(lds + (bufoff) + ldsw + _i * 8192), 16, 0, 0); } while (0)
; #define PG8_LDA(dst, b, h) do { _Pragma("unroll") for (int m = 0; m < 4; ++m) _Pragma("unroll") for (int k = 0; k < 2; ++k) dst[m][k] = *(const PG8_LAS bf16x8*)(lds + PG8_SA(b, h) + aoff + m * 2048 + k * 1024); } while (0)
; #define PG8_WAIT_V(n) asm volatile("s_waitcnt vmcnt(" #n ")" ::: "memory")
; #define PG8_WAIT_L(n) asm volatile("s_waitcnt lgkmcnt(" #n ")" ::: "memory")
; template <class Epi, class Sched, bool ALIGN_EPI = false, bool SP2 = false>
; __device__ __forceinline__ void gemm_phase(PG8_LAS unsigned char* lds, const Gemm g, const Sched& S, const Epi& E) {
;     ...
;         for (int t = 0; t < nt; t += 2) {
;             const bool last = (t == nt - 2);
;             const char* a1 = cA + (size_t)(t + 1) * kstep;
;             const char* a2 = last ? nA : cA + (size_t)(t + 2) * kstep; const char* b2 = last ? nB : cB + (size_t)(t + 2) * kstep;
;             const char* a3 = a2 + kstep; const char* b3 = b2 + kstep;
;             if (last && has_next) S.a_ready(nxt);
;             if constexpr (SP2) {
;             PG8_LDB(B0, 0, 0); PG8_LDB(B1, 0, 1); PG8_SCHED; PG8_LDA(At, 0, 0); PG8_STAGE(PG8_SA(1, 1), a1 + hstep, voffA);
;             PG8_WAIT_V(8); PG8_WAIT_L(0); PG8_BAR; PG8_MMA(0, 0, At, B0); PG8_MMA(0, 1, At, B1); PG8_BAR; PG8_SCHED;
;             PG8_LDA(At, 0, 1); PG8_STAGE(PG8_SB(0, 0), b2, voffB); PG8_STAGE(PG8_SB(0, 1), b2 + hstep, voffB); PG8_STAGE(PG8_SA(0, 0), a2, voffA);
;             PG8_WAIT_V(8); PG8_WAIT_L(0); PG8_BAR; PG8_MMA(1, 0, At, B0); PG8_MMA(1, 1, At, B1); PG8_BAR; PG8_SCHED;
;             PG8_LDB(B0, 1, 0); PG8_LDB(B1, 1, 1); PG8_SCHED; PG8_LDA(At, 1, 0); PG8_STAGE(PG8_SA(0, 1), a2 + hstep, voffA);
;             PG8_WAIT_V(8); PG8_WAIT_L(0); PG8_BAR; PG8_MMA(0, 0, At, B0); PG8_MMA(0, 1, At, B1); PG8_BAR; PG8_SCHED;
;             PG8_LDA(At, 1, 1); PG8_STAGE(PG8_SB(1, 0), b3, voffB); PG8_STAGE(PG8_SB(1, 1), b3 + hstep, voffB); PG8_STAGE(PG8_SA(1, 0), a3, voffA);
;             PG8_WAIT_V(8); PG8_WAIT_L(0); PG8_BAR; PG8_MMA(1, 0, At, B0); PG8_MMA(1, 1, At, B1); PG8_BAR; PG8_SCHED;
;     ...
;         if constexpr (ALIGN_EPI) { if (wr == 0) PG8_BAR; }
	s_add_i32 s59, 0, 0x18000
	s_add_i32 s60, 0, 0x1c000
	ds_read_b128 v[130:133], v246
	ds_read_b128 v[134:137], v246 offset:1024
	ds_read_b128 v[138:141], v246 offset:2048
	ds_read_b128 v[142:145], v246 offset:3072
	ds_read_b128 v[146:149], v247
	ds_read_b128 v[162:165], v247 offset:1024
	ds_read_b128 v[168:171], v247 offset:2048
	ds_read_b128 v[172:175], v247 offset:3072
	s_mov_b32 m0, s36
	s_nop 0
	global_load_lds_dwordx4 v154, s[30:31]
	s_mov_b32 m0, s37
	s_nop 0
	global_load_lds_dwordx4 v152, s[30:31]
	s_add_u32 s30, s30, 0x200000
	s_addc_u32 s31, s31, 0
	s_mov_b32 m0, s42
	ds_read_b128 v[182:185], v180 offset:32768
	ds_read_b128 v[186:189], v180 offset:33792
	ds_read_b128 v[190:193], v180 offset:34816
	ds_read_b128 v[200:203], v180 offset:35840
	ds_read_b128 v[204:207], v180 offset:36864
	ds_read_b128 v[208:211], v180 offset:37888
	ds_read_b128 v[212:215], v180 offset:38912
	ds_read_b128 v[216:219], v180 offset:39936
	global_load_lds_dwordx4 v154, s[30:31]
	s_mov_b32 m0, s43
	s_nop 0
	global_load_lds_dwordx4 v152, s[30:31]
	s_waitcnt vmcnt(8) lgkmcnt(0)
	s_barrier
	v_mfma_f32_16x16x32_bf16 v[126:129], v[130:133], v[182:185], v[126:129]
	v_mfma_f32_16x16x32_bf16 v[122:125], v[138:141], v[182:185], v[122:125]
	v_mfma_f32_16x16x32_bf16 v[118:121], v[130:133], v[190:193], v[118:121]
	v_mfma_f32_16x16x32_bf16 v[114:117], v[138:141], v[190:193], v[114:117]
	v_mfma_f32_16x16x32_bf16 v[94:97], v[130:133], v[204:207], v[94:97]
	v_mfma_f32_16x16x32_bf16 v[90:93], v[138:141], v[204:207], v[90:93]
	v_mfma_f32_16x16x32_bf16 v[82:85], v[130:133], v[212:215], v[82:85]
	v_mfma_f32_16x16x32_bf16 v[74:77], v[138:141], v[212:215], v[74:77]
	v_mfma_f32_16x16x32_bf16 v[126:129], v[134:137], v[186:189], v[126:129]
	v_mfma_f32_16x16x32_bf16 v[122:125], v[142:145], v[186:189], v[122:125]
	v_mfma_f32_16x16x32_bf16 v[118:121], v[134:137], v[200:203], v[118:121]
	v_mfma_f32_16x16x32_bf16 v[114:117], v[142:145], v[200:203], v[114:117]
	v_mfma_f32_16x16x32_bf16 v[94:97], v[134:137], v[208:211], v[94:97]
	v_mfma_f32_16x16x32_bf16 v[90:93], v[142:145], v[208:211], v[90:93]
	v_mfma_f32_16x16x32_bf16 v[82:85], v[134:137], v[216:219], v[82:85]
	v_mfma_f32_16x16x32_bf16 v[74:77], v[142:145], v[216:219], v[74:77]
	v_mfma_f32_16x16x32_bf16 v[110:113], v[146:149], v[182:185], v[110:113]
	v_mfma_f32_16x16x32_bf16 v[106:109], v[168:171], v[182:185], v[106:109]
	v_mfma_f32_16x16x32_bf16 v[102:105], v[146:149], v[190:193], v[102:105]
	v_mfma_f32_16x16x32_bf16 v[98:101], v[168:171], v[190:193], v[98:101]
	v_mfma_f32_16x16x32_bf16 v[86:89], v[146:149], v[204:207], v[86:89]
	v_mfma_f32_16x16x32_bf16 v[78:81], v[168:171], v[204:207], v[78:81]
	v_mfma_f32_16x16x32_bf16 v[70:73], v[146:149], v[212:215], v[70:73]
	v_mfma_f32_16x16x32_bf16 v[66:69], v[168:171], v[212:215], v[66:69]
	v_mfma_f32_16x16x32_bf16 v[110:113], v[162:165], v[186:189], v[110:113]
	v_mfma_f32_16x16x32_bf16 v[106:109], v[172:175], v[186:189], v[106:109]
	v_mfma_f32_16x16x32_bf16 v[102:105], v[162:165], v[200:203], v[102:105]
	v_mfma_f32_16x16x32_bf16 v[98:101], v[172:175], v[200:203], v[98:101]
	v_mfma_f32_16x16x32_bf16 v[86:89], v[162:165], v[208:211], v[86:89]
	v_mfma_f32_16x16x32_bf16 v[78:81], v[172:175], v[208:211], v[78:81]
	v_mfma_f32_16x16x32_bf16 v[70:73], v[162:165], v[216:219], v[70:73]
	v_mfma_f32_16x16x32_bf16 v[66:69], v[172:175], v[216:219], v[66:69]
	s_barrier
	s_add_i32 s30, s59, s34
	s_add_i32 m0, s30, 0xffffff80
	ds_read_b128 v[182:185], v180 offset:49152
	ds_read_b128 v[186:189], v180 offset:50176
	ds_read_b128 v[190:193], v180 offset:51200
	ds_read_b128 v[200:203], v180 offset:52224
	ds_read_b128 v[204:207], v180 offset:53248
	ds_read_b128 v[208:211], v180 offset:54272
	ds_read_b128 v[212:215], v180 offset:55296
	ds_read_b128 v[216:219], v180 offset:56320
	global_load_lds_dwordx4 v158, s[28:29] offset:128
	s_add_i32 m0, s30, 0x1f80
	s_add_i32 s30, s60, s34
	global_load_lds_dwordx4 v150, s[28:29] offset:128
	s_add_u32 s28, s28, 0x200080
	s_addc_u32 s29, s29, 0
	s_mov_b32 m0, s30
	s_nop 0
	global_load_lds_dwordx4 v158, s[28:29]
	s_add_i32 m0, s30, 0x2000
	s_nop 0
	global_load_lds_dwordx4 v150, s[28:29]
	s_waitcnt vmcnt(6) lgkmcnt(0)
	s_barrier
	v_mfma_f32_16x16x32_bf16 v[62:65], v[130:133], v[182:185], v[62:65]
	v_mfma_f32_16x16x32_bf16 v[58:61], v[138:141], v[182:185], v[58:61]
	v_mfma_f32_16x16x32_bf16 v[50:53], v[130:133], v[190:193], v[50:53]
	v_mfma_f32_16x16x32_bf16 v[42:45], v[138:141], v[190:193], v[42:45]
	v_mfma_f32_16x16x32_bf16 v[34:37], v[130:133], v[204:207], v[34:37]
	v_mfma_f32_16x16x32_bf16 v[26:29], v[138:141], v[204:207], v[26:29]
	v_mfma_f32_16x16x32_bf16 v[18:21], v[130:133], v[212:215], v[18:21]
	v_mfma_f32_16x16x32_bf16 v[10:13], v[138:141], v[212:215], v[10:13]
	v_mfma_f32_16x16x32_bf16 v[62:65], v[134:137], v[186:189], v[62:65]
	v_mfma_f32_16x16x32_bf16 v[58:61], v[142:145], v[186:189], v[58:61]
	v_mfma_f32_16x16x32_bf16 v[50:53], v[134:137], v[200:203], v[50:53]
	v_mfma_f32_16x16x32_bf16 v[42:45], v[142:145], v[200:203], v[42:45]
	v_mfma_f32_16x16x32_bf16 v[34:37], v[134:137], v[208:211], v[34:37]
	v_mfma_f32_16x16x32_bf16 v[26:29], v[142:145], v[208:211], v[26:29]
	v_mfma_f32_16x16x32_bf16 v[18:21], v[134:137], v[216:219], v[18:21]
	v_mfma_f32_16x16x32_bf16 v[10:13], v[142:145], v[216:219], v[10:13]
	v_mfma_f32_16x16x32_bf16 v[54:57], v[146:149], v[182:185], v[54:57]
	v_mfma_f32_16x16x32_bf16 v[46:49], v[168:171], v[182:185], v[46:49]
	v_mfma_f32_16x16x32_bf16 v[38:41], v[146:149], v[190:193], v[38:41]
	v_mfma_f32_16x16x32_bf16 v[30:33], v[168:171], v[190:193], v[30:33]
	v_mfma_f32_16x16x32_bf16 v[22:25], v[146:149], v[204:207], v[22:25]
	v_mfma_f32_16x16x32_bf16 v[14:17], v[168:171], v[204:207], v[14:17]
	v_mfma_f32_16x16x32_bf16 v[6:9], v[146:149], v[212:215], v[6:9]
	v_mfma_f32_16x16x32_bf16 v[2:5], v[168:171], v[212:215], v[2:5]
	v_mfma_f32_16x16x32_bf16 v[54:57], v[162:165], v[186:189], v[54:57]
	v_mfma_f32_16x16x32_bf16 v[46:49], v[172:175], v[186:189], v[46:49]
	v_mfma_f32_16x16x32_bf16 v[38:41], v[162:165], v[200:203], v[38:41]
	v_mfma_f32_16x16x32_bf16 v[30:33], v[172:175], v[200:203], v[30:33]
	v_mfma_f32_16x16x32_bf16 v[22:25], v[162:165], v[208:211], v[22:25]
	v_mfma_f32_16x16x32_bf16 v[14:17], v[172:175], v[208:211], v[14:17]
	v_mfma_f32_16x16x32_bf16 v[6:9], v[162:165], v[216:219], v[6:9]
	v_mfma_f32_16x16x32_bf16 v[2:5], v[172:175], v[216:219], v[2:5]
	s_barrier
	s_add_i32 s58, s58, 2
	s_add_u32 s0, s0, 0x100
	s_addc_u32 s1, s1, 0
	s_add_u32 s56, s56, 0x100
	s_addc_u32 s57, s57, 0
	s_cmpk_gt_u32 s58, 0x7d
	s_cbranch_scc0 .LBB0_880
	s_and_b64 vcc, exec, s[14:15]
	s_cbranch_vccz .LBB0_883
	s_barrier
